# P2 gate loop: removed the dead denormal pre-scaling and inf-select of __logf(1+exp(-|z|)) (argument in [1,2], results bit-identical)
# speedup vs baseline: 1.0022x; 1.0009x over previous
; #define LAS __attribute__((address_space(3)))
; DI void p2_unit(int chunk, const Params& p, LAS unsigned char* lds) {
;     ...
;     { const int col = tid & 255, half = tid >> 8, t0 = 32 * half, t0u = __builtin_amdgcn_readfirstlane(t0);
;       LAS float* tots = (LAS float*)(lds + L2_DEC) + 256;
;       float w2c[16];
; #pragma unroll
;       for (int r = 0; r < 16; ++r) w2c[r] = p.gla_w2[r * 256 + col];
;       const float bgc = p.gla_bg[col];
;       bf16_t* pq = proj + (size_t)(tok0 + t0) * NPROJ + C_GQ + col; bf16_t* pk = proj + (size_t)(tok0 + t0) * NPROJ + C_GK + col;
;       bf16_t qv32[32], kv32[32];
; #pragma unroll
;       for (int j2 = 0; j2 < 32; ++j2) { qv32[j2] = pq[(size_t)j2 * NPROJ]; kv32[j2] = pk[(size_t)j2 * NPROJ]; }
.LBB0_354:
	v_and_b32_e32 v219, 0xff, v146
	v_lshlrev_b32_e32 v66, 2, v219
	v_lshl_add_u64 v[0:1], s[30:31], 0, v[66:67]
	v_add_co_u32_e32 v2, vcc, 0x1000, v0
	global_load_dword v19, v66, s[30:31]
	global_load_dword v21, v66, s[30:31] offset:1024
	global_load_dword v20, v66, s[30:31] offset:2048
	global_load_dword v18, v66, s[30:31] offset:3072
	v_addc_co_u32_e32 v3, vcc, 0, v1, vcc
	global_load_dword v23, v[2:3], off
	global_load_dword v25, v[2:3], off offset:1024
	global_load_dword v24, v[2:3], off offset:2048
	global_load_dword v22, v[2:3], off offset:3072
	v_add_co_u32_e32 v2, vcc, 0x2000, v0
	v_ashrrev_i32_e32 v69, 3, v146
	s_nop 0
	v_addc_co_u32_e32 v3, vcc, 0, v1, vcc
	v_add_co_u32_e32 v0, vcc, 0x3000, v0
	v_and_b32_e32 v204, 0xffffffe0, v69
	s_nop 0
	v_addc_co_u32_e32 v1, vcc, 0, v1, vcc
	global_load_dword v27, v[2:3], off
	global_load_dword v32, v[2:3], off offset:1024
	global_load_dword v28, v[2:3], off offset:2048
	global_load_dword v26, v[2:3], off offset:3072
	global_load_dword v30, v[0:1], off
	global_load_dword v33, v[0:1], off offset:1024
	global_load_dword v31, v[0:1], off offset:2048
	global_load_dword v29, v[0:1], off offset:3072
	v_add_u32_e32 v2, s52, v204
	v_mov_b64_e32 v[0:1], s[14:15]
	v_mad_i64_i32 v[0:1], s[0:1], v2, s53, v[0:1]
	v_lshlrev_b32_e32 v2, 1, v219
	v_mov_b32_e32 v3, v67
	v_lshl_add_u64 v[16:17], v[0:1], 0, v[2:3]
	s_movk_i32 s0, 0x2000
	v_readlane_b32 s36, v254, 0
	v_add_co_u32_e32 v0, vcc, s0, v16
	v_readlane_b32 s37, v254, 1
	s_nop 0
	v_addc_co_u32_e32 v1, vcc, 0, v17, vcc
	s_movk_i32 s0, 0x4000
	v_readlane_b32 s40, v254, 4
	v_readlane_b32 s41, v254, 5
	global_load_dword v34, v66, s[36:37]
	global_load_ushort v218, v[16:17], off offset:3072
	global_load_ushort v217, v[16:17], off offset:3584
	global_load_ushort v216, v[0:1], off offset:1536
	global_load_ushort v215, v[0:1], off offset:2048
	v_add_co_u32_e32 v0, vcc, s0, v16
	s_movk_i32 s0, 0x5000
	s_nop 0
	v_addc_co_u32_e32 v1, vcc, 0, v17, vcc
	global_load_ushort v214, v[0:1], off
	global_load_ushort v212, v[0:1], off offset:512
	v_add_co_u32_e32 v0, vcc, s0, v16
	s_movk_i32 s0, 0x7000
	s_nop 0
	v_addc_co_u32_e32 v1, vcc, 0, v17, vcc
	global_load_ushort v213, v[0:1], off offset:2560
	global_load_ushort v211, v[0:1], off offset:3072
	v_add_co_u32_e32 v0, vcc, s0, v16
	s_mov_b32 s0, 0x8000
	s_nop 0
	v_addc_co_u32_e32 v1, vcc, 0, v17, vcc
	global_load_ushort v210, v[0:1], off offset:1024
	global_load_ushort v209, v[0:1], off offset:1536
	v_add_co_u32_e32 v0, vcc, s0, v16
	s_mov_b32 s0, 0x9000
	s_nop 0
	v_addc_co_u32_e32 v1, vcc, 0, v17, vcc
	global_load_ushort v207, v[0:1], off offset:3584
	v_add_co_u32_e32 v0, vcc, s0, v16
	s_mov_b32 s0, 0xa000
	s_nop 0
	v_addc_co_u32_e32 v1, vcc, 0, v17, vcc
	global_load_ushort v205, v[0:1], off
	v_add_co_u32_e32 v0, vcc, s0, v16
	s_mov_b32 s0, 0xc000
	s_nop 0
	v_addc_co_u32_e32 v1, vcc, 0, v17, vcc
	global_load_ushort v203, v[0:1], off offset:2048
	global_load_ushort v201, v[0:1], off offset:2560
	v_add_co_u32_e32 v0, vcc, s0, v16
	s_mov_b32 s0, 0xd000
	s_nop 0
	v_addc_co_u32_e32 v1, vcc, 0, v17, vcc
	global_load_ushort v202, v[0:1], off offset:512
	global_load_ushort v200, v[0:1], off offset:1024
	v_add_co_u32_e32 v0, vcc, s0, v16
	s_mov_b32 s0, 0xf000
	s_nop 0
	v_addc_co_u32_e32 v1, vcc, 0, v17, vcc
	global_load_ushort v199, v[0:1], off offset:3072
	global_load_ushort v198, v[0:1], off offset:3584
	v_add_co_u32_e32 v0, vcc, s0, v16
	s_mov_b32 s0, 0x11000
	s_nop 0
	v_addc_co_u32_e32 v1, vcc, 0, v17, vcc
	global_load_ushort v197, v[0:1], off offset:1536
	global_load_ushort v196, v[0:1], off offset:2048
	v_add_co_u32_e32 v0, vcc, s0, v16
	s_mov_b32 s0, 0x12000
	s_nop 0
	v_addc_co_u32_e32 v1, vcc, 0, v17, vcc
	global_load_ushort v195, v[0:1], off
	global_load_ushort v193, v[0:1], off offset:512
	v_add_co_u32_e32 v0, vcc, s0, v16
	s_mov_b32 s0, 0x14000
	s_nop 0
	v_addc_co_u32_e32 v1, vcc, 0, v17, vcc
	global_load_ushort v194, v[0:1], off offset:2560
	global_load_ushort v192, v[0:1], off offset:3072
	v_add_co_u32_e32 v0, vcc, s0, v16
	s_mov_b32 s0, 0x15000
	s_nop 0
	v_addc_co_u32_e32 v1, vcc, 0, v17, vcc
	global_load_ushort v191, v[0:1], off offset:1024
	global_load_ushort v190, v[0:1], off offset:1536
	v_add_co_u32_e32 v0, vcc, s0, v16
	s_mov_b32 s0, 0x16000
	s_nop 0
	v_addc_co_u32_e32 v1, vcc, 0, v17, vcc
	global_load_ushort v189, v[0:1], off offset:3584
	v_add_co_u32_e32 v0, vcc, s0, v16
	s_mov_b32 s0, 0x17000
	s_nop 0
	v_addc_co_u32_e32 v1, vcc, 0, v17, vcc
	global_load_ushort v188, v[0:1], off
	v_add_co_u32_e32 v0, vcc, s0, v16
	s_mov_b32 s0, 0x19000
	s_nop 0
	v_addc_co_u32_e32 v1, vcc, 0, v17, vcc
	global_load_ushort v187, v[0:1], off offset:2048
	global_load_ushort v185, v[0:1], off offset:2560
	v_add_co_u32_e32 v0, vcc, s0, v16
	s_mov_b32 s0, 0x1a000
	s_nop 0
	v_addc_co_u32_e32 v1, vcc, 0, v17, vcc
	global_load_ushort v186, v[0:1], off offset:512
	global_load_ushort v184, v[0:1], off offset:1024
	v_add_co_u32_e32 v0, vcc, s0, v16
	s_mov_b32 s0, 0x1c000
	s_nop 0
	v_addc_co_u32_e32 v1, vcc, 0, v17, vcc
	global_load_ushort v183, v[0:1], off offset:3072
	global_load_ushort v182, v[0:1], off offset:3584
	v_add_co_u32_e32 v0, vcc, s0, v16
	s_mov_b32 s0, 0x1e000
	s_nop 0
	v_addc_co_u32_e32 v1, vcc, 0, v17, vcc
	global_load_ushort v181, v[0:1], off offset:1536
	global_load_ushort v180, v[0:1], off offset:2048
	v_add_co_u32_e32 v0, vcc, s0, v16
	s_mov_b32 s0, 0x1f000
	s_nop 0
	v_addc_co_u32_e32 v1, vcc, 0, v17, vcc
	global_load_ushort v179, v[0:1], off
	global_load_ushort v177, v[0:1], off offset:512
	v_add_co_u32_e32 v0, vcc, s0, v16
	s_mov_b32 s0, 0x21000
	s_nop 0
	v_addc_co_u32_e32 v1, vcc, 0, v17, vcc
; DI float logsig_fast(float z) { return fminf(z, 0.f) - __logf(1.0f + __expf(-fabsf(z))); }
; DI void p2_unit(int chunk, const Params& p, LAS unsigned char* lds) {
;     ...
;       bf16_t* pq = proj + (size_t)(tok0 + t0) * NPROJ + C_GQ + col; bf16_t* pk = proj + (size_t)(tok0 + t0) * NPROJ + C_GK + col;
;       bf16_t qv32[32], kv32[32];
; #pragma unroll
;       for (int j2 = 0; j2 < 32; ++j2) { qv32[j2] = pq[(size_t)j2 * NPROJ]; kv32[j2] = pk[(size_t)j2 * NPROJ]; }
;       float lc[32]; float bc = 0.f;
; #pragma unroll
;       for (int j2 = 0; j2 < 32; ++j2) { const f32x4* ar = (const f32x4*)(aux + (size_t)(tok0 + t0u + j2) * 32 + 8);
;           float z = bgc;
; #pragma unroll
;           for (int r4 = 0; r4 < 4; ++r4) { const f32x4 a = ar[r4]; z += a.x * w2c[4 * r4] + a.y * w2c[4 * r4 + 1] + a.z * w2c[4 * r4 + 2] + a.w * w2c[4 * r4 + 3]; }
;           bc += logsig_fast(z) * (1.0f / 16.0f); lc[j2] = bc; }
	global_load_ushort v178, v[0:1], off offset:2560
	global_load_ushort v176, v[0:1], off offset:3072
	v_add_co_u32_e32 v0, vcc, s0, v16
	s_mov_b32 s0, 0x22000
	s_nop 0
	v_addc_co_u32_e32 v1, vcc, 0, v17, vcc
	global_load_ushort v175, v[0:1], off offset:1024
	global_load_ushort v174, v[0:1], off offset:1536
	v_add_co_u32_e32 v0, vcc, s0, v16
	s_mov_b32 s0, 0x23000
	s_nop 0
	v_addc_co_u32_e32 v1, vcc, 0, v17, vcc
	global_load_ushort v173, v[0:1], off offset:3584
	v_add_co_u32_e32 v0, vcc, s0, v16
	s_mov_b32 s0, 0x24000
	s_nop 0
	v_addc_co_u32_e32 v1, vcc, 0, v17, vcc
	global_load_ushort v172, v[0:1], off
	v_add_co_u32_e32 v0, vcc, s0, v16
	s_mov_b32 s0, 0x26000
	s_nop 0
	v_addc_co_u32_e32 v1, vcc, 0, v17, vcc
	global_load_ushort v171, v[0:1], off offset:2048
	global_load_ushort v170, v[0:1], off offset:2560
	v_add_co_u32_e32 v0, vcc, s0, v16
	s_mov_b32 s0, 0x27000
	s_nop 0
	v_addc_co_u32_e32 v1, vcc, 0, v17, vcc
	global_load_ushort v169, v[0:1], off offset:512
	global_load_ushort v168, v[0:1], off offset:1024
	v_add_co_u32_e32 v0, vcc, s0, v16
	s_mov_b32 s0, 0x29000
	s_nop 0
	v_addc_co_u32_e32 v1, vcc, 0, v17, vcc
	global_load_ushort v167, v[0:1], off offset:3072
	global_load_ushort v166, v[0:1], off offset:3584
	v_add_co_u32_e32 v0, vcc, s0, v16
	s_mov_b32 s0, 0x2b000
	s_nop 0
	v_addc_co_u32_e32 v1, vcc, 0, v17, vcc
	global_load_ushort v161, v[0:1], off offset:1536
	global_load_ushort v160, v[0:1], off offset:2048
	v_add_co_u32_e32 v0, vcc, s0, v16
	s_mov_b32 s0, 0x2c000
	s_nop 0
	v_addc_co_u32_e32 v1, vcc, 0, v17, vcc
	global_load_ushort v159, v[0:1], off
	global_load_ushort v158, v[0:1], off offset:512
	v_add_co_u32_e32 v0, vcc, s0, v16
	s_mov_b32 s0, 0x2e000
	s_nop 0
	v_addc_co_u32_e32 v1, vcc, 0, v17, vcc
	global_load_ushort v157, v[0:1], off offset:2560
	global_load_ushort v156, v[0:1], off offset:3072
	v_add_co_u32_e32 v0, vcc, s0, v16
	s_mov_b32 s0, 0x2f000
	s_nop 0
	v_addc_co_u32_e32 v1, vcc, 0, v17, vcc
	global_load_ushort v155, v[0:1], off offset:1024
	global_load_ushort v154, v[0:1], off offset:1536
	v_add_co_u32_e32 v0, vcc, s0, v16
	s_mov_b32 s0, 0x30000
	s_nop 0
	v_addc_co_u32_e32 v1, vcc, 0, v17, vcc
	global_load_ushort v153, v[0:1], off offset:3584
	v_add_co_u32_e32 v0, vcc, s0, v16
	s_mov_b32 s0, 0x31000
	s_nop 0
	v_addc_co_u32_e32 v1, vcc, 0, v17, vcc
	global_load_ushort v152, v[0:1], off
	v_add_co_u32_e32 v0, vcc, s0, v16
	s_mov_b32 s0, 0x33000
	s_nop 0
	v_addc_co_u32_e32 v1, vcc, 0, v17, vcc
	global_load_ushort v151, v[0:1], off offset:2048
	global_load_ushort v150, v[0:1], off offset:2560
	v_add_co_u32_e32 v0, vcc, s0, v16
	v_readfirstlane_b32 s0, v204
	s_add_i32 s40, s0, s52
	s_ashr_i32 s41, s40, 31
	s_lshl_b64 s[0:1], s[40:41], 7
	s_add_u32 s0, s60, s0
	v_addc_co_u32_e32 v1, vcc, 0, v17, vcc
	s_addc_u32 s1, s61, s1
	global_load_ushort v149, v[0:1], off offset:512
	global_load_ushort v148, v[0:1], off offset:1024
	s_nop 0
	s_mov_b64 s[98:99], s[0:1]
	global_load_dwordx4 v[70:73], v67, s[98:99] offset:80
	global_load_dwordx4 v[74:77], v67, s[98:99] offset:64
	global_load_dwordx4 v[78:81], v67, s[98:99] offset:48
	global_load_dwordx4 v[82:85], v67, s[98:99] offset:32
	global_load_dwordx4 v[0:3], v67, s[98:99] offset:208
	global_load_dwordx4 v[4:7], v67, s[98:99] offset:192
	global_load_dwordx4 v[8:11], v67, s[98:99] offset:176
	global_load_dwordx4 v[12:15], v67, s[98:99] offset:160
	v_readlane_b32 s38, v254, 2
	v_readlane_b32 s39, v254, 3
	s_mov_b32 s0, 0x3d800000
	v_readlane_b32 s42, v254, 6
	v_readlane_b32 s43, v254, 7
	v_readlane_b32 s44, v254, 8
	v_readlane_b32 s45, v254, 9
	v_readlane_b32 s46, v254, 10
	v_readlane_b32 s47, v254, 11
	v_readlane_b32 s48, v254, 12
	v_readlane_b32 s49, v254, 13
	v_readlane_b32 s50, v254, 14
	v_readlane_b32 s51, v254, 15
	s_waitcnt vmcnt(7)
	v_mul_f32_e32 v71, v33, v71
	s_waitcnt vmcnt(6)
	v_mul_f32_e32 v75, v32, v75
	s_waitcnt vmcnt(5)
	v_mul_f32_e32 v79, v25, v79
	s_waitcnt vmcnt(4)
	v_mul_f32_e32 v83, v21, v83
	v_fmac_f32_e32 v83, v19, v82
	v_fmac_f32_e32 v83, v20, v84
	v_fmac_f32_e32 v79, v23, v78
	v_fmac_f32_e32 v83, v18, v85
	v_fmac_f32_e32 v79, v24, v80
	v_fmac_f32_e32 v75, v27, v74
	v_add_f32_e32 v82, v34, v83
	v_fmac_f32_e32 v79, v22, v81
	v_fmac_f32_e32 v75, v28, v76
	v_fmac_f32_e32 v71, v30, v70
	v_add_f32_e32 v78, v82, v79
	v_fmac_f32_e32 v75, v26, v77
	v_fmac_f32_e32 v71, v31, v72
	v_add_f32_e32 v74, v78, v75
	v_fmac_f32_e32 v71, v29, v73
	v_add_f32_e32 v70, v74, v71
	v_min_f32_e32 v71, 0, v70
	v_mul_f32_e64 v70, |v70|, s59
	v_exp_f32_e32 v70, v70
	s_nop 0
	v_add_f32_e32 v70, 1.0, v70
	v_log_f32_e32 v70, v70
	s_nop 0
	v_mul_f32_e32 v72, 0x3f317217, v70
	v_fma_f32 v72, v70, s87, -v72
	v_fmac_f32_e32 v72, 0x3377d1cf, v70
	v_fmac_f32_e32 v72, 0x3f317217, v70
	v_sub_f32_e32 v70, v71, v72
	v_fma_f32 v220, v70, s0, 0
	global_load_dwordx4 v[70:73], v67, s[98:99] offset:336
	global_load_dwordx4 v[74:77], v67, s[98:99] offset:320
	global_load_dwordx4 v[78:81], v67, s[98:99] offset:304
	global_load_dwordx4 v[82:85], v67, s[98:99] offset:288
	s_waitcnt vmcnt(7)
	v_mul_f32_e32 v1, v33, v1
	s_waitcnt vmcnt(6)
	v_mul_f32_e32 v5, v32, v5
	s_waitcnt vmcnt(5)
	v_mul_f32_e32 v9, v25, v9
	s_waitcnt vmcnt(4)
; DI float logsig_fast(float z) { return fminf(z, 0.f) - __logf(1.0f + __expf(-fabsf(z))); }
; DI void p2_unit(int chunk, const Params& p, LAS unsigned char* lds) {
;     ...
;       for (int j2 = 0; j2 < 32; ++j2) { const f32x4* ar = (const f32x4*)(aux + (size_t)(tok0 + t0u + j2) * 32 + 8);
;           float z = bgc;
; #pragma unroll
;           for (int r4 = 0; r4 < 4; ++r4) { const f32x4 a = ar[r4]; z += a.x * w2c[4 * r4] + a.y * w2c[4 * r4 + 1] + a.z * w2c[4 * r4 + 2] + a.w * w2c[4 * r4 + 3]; }
;           bc += logsig_fast(z) * (1.0f / 16.0f); lc[j2] = bc; }
	v_mul_f32_e32 v13, v21, v13
	v_fmac_f32_e32 v13, v19, v12
	v_fmac_f32_e32 v13, v20, v14
	v_fmac_f32_e32 v9, v23, v8
	v_fmac_f32_e32 v13, v18, v15
	v_fmac_f32_e32 v9, v24, v10
	v_fmac_f32_e32 v5, v27, v4
	v_add_f32_e32 v12, v34, v13
	v_fmac_f32_e32 v9, v22, v11
	v_fmac_f32_e32 v5, v28, v6
	v_fmac_f32_e32 v1, v30, v0
	v_add_f32_e32 v8, v12, v9
	v_fmac_f32_e32 v5, v26, v7
	v_fmac_f32_e32 v1, v31, v2
	v_add_f32_e32 v4, v8, v5
	v_fmac_f32_e32 v1, v29, v3
	v_add_f32_e32 v0, v4, v1
	v_min_f32_e32 v1, 0, v0
	v_mul_f32_e64 v0, |v0|, s59
	v_exp_f32_e32 v0, v0
	s_nop 0
	v_add_f32_e32 v0, 1.0, v0
	v_log_f32_e32 v0, v0
	s_nop 0
	v_mul_f32_e32 v2, 0x3f317217, v0
	v_fma_f32 v2, v0, s87, -v2
	v_fmac_f32_e32 v2, 0x3377d1cf, v0
	v_fmac_f32_e32 v2, 0x3f317217, v0
	v_sub_f32_e32 v0, v1, v2
	v_fmamk_f32 v221, v0, 0x3d800000, v220
	global_load_dwordx4 v[0:3], v67, s[98:99] offset:464
	global_load_dwordx4 v[4:7], v67, s[98:99] offset:448
	global_load_dwordx4 v[8:11], v67, s[98:99] offset:432
	global_load_dwordx4 v[12:15], v67, s[98:99] offset:416
	s_waitcnt vmcnt(7)
	v_mul_f32_e32 v71, v33, v71
	s_waitcnt vmcnt(6)
	v_mul_f32_e32 v75, v32, v75
	s_waitcnt vmcnt(5)
	v_mul_f32_e32 v79, v25, v79
	s_waitcnt vmcnt(4)
	v_mul_f32_e32 v83, v21, v83
	v_fmac_f32_e32 v83, v19, v82
	v_fmac_f32_e32 v83, v20, v84
	v_fmac_f32_e32 v79, v23, v78
	v_fmac_f32_e32 v83, v18, v85
	v_fmac_f32_e32 v79, v24, v80
	v_fmac_f32_e32 v75, v27, v74
	v_add_f32_e32 v82, v34, v83
	v_fmac_f32_e32 v79, v22, v81
	v_fmac_f32_e32 v75, v28, v76
	v_fmac_f32_e32 v71, v30, v70
	v_add_f32_e32 v78, v82, v79
	v_fmac_f32_e32 v75, v26, v77
	v_fmac_f32_e32 v71, v31, v72
	v_add_f32_e32 v74, v78, v75
	v_fmac_f32_e32 v71, v29, v73
	v_add_f32_e32 v70, v74, v71
	v_min_f32_e32 v71, 0, v70
	v_mul_f32_e64 v70, |v70|, s59
	v_exp_f32_e32 v70, v70
	s_nop 0
	v_add_f32_e32 v70, 1.0, v70
	v_log_f32_e32 v70, v70
	s_nop 0
	v_mul_f32_e32 v72, 0x3f317217, v70
	v_fma_f32 v72, v70, s87, -v72
	v_fmac_f32_e32 v72, 0x3377d1cf, v70
	v_fmac_f32_e32 v72, 0x3f317217, v70
	v_sub_f32_e32 v70, v71, v72
	v_fmamk_f32 v222, v70, 0x3d800000, v221
	global_load_dwordx4 v[70:73], v67, s[98:99] offset:592
	global_load_dwordx4 v[74:77], v67, s[98:99] offset:576
	global_load_dwordx4 v[78:81], v67, s[98:99] offset:560
	global_load_dwordx4 v[82:85], v67, s[98:99] offset:544
	s_waitcnt vmcnt(7)
	v_mul_f32_e32 v1, v33, v1
	s_waitcnt vmcnt(6)
	v_mul_f32_e32 v5, v32, v5
	s_waitcnt vmcnt(5)
	v_mul_f32_e32 v9, v25, v9
	s_waitcnt vmcnt(4)
	v_mul_f32_e32 v13, v21, v13
	v_fmac_f32_e32 v13, v19, v12
	v_fmac_f32_e32 v13, v20, v14
	v_fmac_f32_e32 v9, v23, v8
	v_fmac_f32_e32 v13, v18, v15
	v_fmac_f32_e32 v9, v24, v10
	v_fmac_f32_e32 v5, v27, v4
	v_add_f32_e32 v12, v34, v13
	v_fmac_f32_e32 v9, v22, v11
	v_fmac_f32_e32 v5, v28, v6
	v_fmac_f32_e32 v1, v30, v0
	v_add_f32_e32 v8, v12, v9
	v_fmac_f32_e32 v5, v26, v7
	v_fmac_f32_e32 v1, v31, v2
	v_add_f32_e32 v4, v8, v5
	v_fmac_f32_e32 v1, v29, v3
	v_add_f32_e32 v0, v4, v1
	v_min_f32_e32 v1, 0, v0
	v_mul_f32_e64 v0, |v0|, s59
	v_exp_f32_e32 v0, v0
	s_nop 0
	v_add_f32_e32 v0, 1.0, v0
	v_log_f32_e32 v0, v0
	s_nop 0
	v_mul_f32_e32 v2, 0x3f317217, v0
	v_fma_f32 v2, v0, s87, -v2
	v_fmac_f32_e32 v2, 0x3377d1cf, v0
	v_fmac_f32_e32 v2, 0x3f317217, v0
	v_sub_f32_e32 v0, v1, v2
	v_fmamk_f32 v223, v0, 0x3d800000, v222
	global_load_dwordx4 v[0:3], v67, s[98:99] offset:720
	global_load_dwordx4 v[4:7], v67, s[98:99] offset:704
	global_load_dwordx4 v[8:11], v67, s[98:99] offset:688
	global_load_dwordx4 v[12:15], v67, s[98:99] offset:672
	s_waitcnt vmcnt(7)
	v_mul_f32_e32 v71, v33, v71
	s_waitcnt vmcnt(6)
	v_mul_f32_e32 v75, v32, v75
	s_waitcnt vmcnt(5)
	v_mul_f32_e32 v79, v25, v79
	s_waitcnt vmcnt(4)
	v_mul_f32_e32 v83, v21, v83
	v_fmac_f32_e32 v83, v19, v82
	v_fmac_f32_e32 v83, v20, v84
	v_fmac_f32_e32 v79, v23, v78
	v_fmac_f32_e32 v83, v18, v85
	v_fmac_f32_e32 v79, v24, v80
	v_fmac_f32_e32 v75, v27, v74
	v_add_f32_e32 v82, v34, v83
	v_fmac_f32_e32 v79, v22, v81
	v_fmac_f32_e32 v75, v28, v76
	v_fmac_f32_e32 v71, v30, v70
	v_add_f32_e32 v78, v82, v79
	v_fmac_f32_e32 v75, v26, v77
	v_fmac_f32_e32 v71, v31, v72
	v_add_f32_e32 v74, v78, v75
	v_fmac_f32_e32 v71, v29, v73
	v_add_f32_e32 v70, v74, v71
	v_min_f32_e32 v71, 0, v70
	v_mul_f32_e64 v70, |v70|, s59
	v_exp_f32_e32 v70, v70
	s_nop 0
	v_add_f32_e32 v70, 1.0, v70
	v_log_f32_e32 v70, v70
	s_nop 0
	v_mul_f32_e32 v72, 0x3f317217, v70
	v_fma_f32 v72, v70, s87, -v72
	v_fmac_f32_e32 v72, 0x3377d1cf, v70
	v_fmac_f32_e32 v72, 0x3f317217, v70
	v_sub_f32_e32 v70, v71, v72
	v_fmamk_f32 v224, v70, 0x3d800000, v223
	global_load_dwordx4 v[70:73], v67, s[98:99] offset:848
	global_load_dwordx4 v[74:77], v67, s[98:99] offset:832
	global_load_dwordx4 v[78:81], v67, s[98:99] offset:816
	global_load_dwordx4 v[82:85], v67, s[98:99] offset:800
	s_waitcnt vmcnt(7)
	v_mul_f32_e32 v1, v33, v1
	s_waitcnt vmcnt(6)
	v_mul_f32_e32 v5, v32, v5
	s_waitcnt vmcnt(5)
	v_mul_f32_e32 v9, v25, v9
	s_waitcnt vmcnt(4)
	v_mul_f32_e32 v13, v21, v13
	v_fmac_f32_e32 v13, v19, v12
	v_fmac_f32_e32 v13, v20, v14
	v_fmac_f32_e32 v9, v23, v8
	v_fmac_f32_e32 v13, v18, v15
	v_fmac_f32_e32 v9, v24, v10
	v_fmac_f32_e32 v5, v27, v4
	v_add_f32_e32 v12, v34, v13
	v_fmac_f32_e32 v9, v22, v11
	v_fmac_f32_e32 v5, v28, v6
	v_fmac_f32_e32 v1, v30, v0
	v_add_f32_e32 v8, v12, v9
	v_fmac_f32_e32 v5, v26, v7
	v_fmac_f32_e32 v1, v31, v2
	v_add_f32_e32 v4, v8, v5
	v_fmac_f32_e32 v1, v29, v3
	v_add_f32_e32 v0, v4, v1
	v_min_f32_e32 v1, 0, v0
	v_mul_f32_e64 v0, |v0|, s59
	v_exp_f32_e32 v0, v0
	s_nop 0
	v_add_f32_e32 v0, 1.0, v0
	v_log_f32_e32 v0, v0
	s_nop 0
	v_mul_f32_e32 v2, 0x3f317217, v0
	v_fma_f32 v2, v0, s87, -v2
	v_fmac_f32_e32 v2, 0x3377d1cf, v0
	v_fmac_f32_e32 v2, 0x3f317217, v0
	v_sub_f32_e32 v0, v1, v2
	v_fmamk_f32 v225, v0, 0x3d800000, v224
	global_load_dwordx4 v[0:3], v67, s[98:99] offset:976
	global_load_dwordx4 v[4:7], v67, s[98:99] offset:960
	global_load_dwordx4 v[8:11], v67, s[98:99] offset:944
	global_load_dwordx4 v[12:15], v67, s[98:99] offset:928
	s_waitcnt vmcnt(7)
; DI float logsig_fast(float z) { return fminf(z, 0.f) - __logf(1.0f + __expf(-fabsf(z))); }
; DI void p2_unit(int chunk, const Params& p, LAS unsigned char* lds) {
;     ...
;       for (int j2 = 0; j2 < 32; ++j2) { const f32x4* ar = (const f32x4*)(aux + (size_t)(tok0 + t0u + j2) * 32 + 8);
;           float z = bgc;
; #pragma unroll
;           for (int r4 = 0; r4 < 4; ++r4) { const f32x4 a = ar[r4]; z += a.x * w2c[4 * r4] + a.y * w2c[4 * r4 + 1] + a.z * w2c[4 * r4 + 2] + a.w * w2c[4 * r4 + 3]; }
;           bc += logsig_fast(z) * (1.0f / 16.0f); lc[j2] = bc; }
	v_mul_f32_e32 v71, v33, v71
	s_waitcnt vmcnt(6)
	v_mul_f32_e32 v75, v32, v75
	s_waitcnt vmcnt(5)
	v_mul_f32_e32 v79, v25, v79
	s_waitcnt vmcnt(4)
	v_mul_f32_e32 v83, v21, v83
	v_fmac_f32_e32 v83, v19, v82
	v_fmac_f32_e32 v83, v20, v84
	v_fmac_f32_e32 v79, v23, v78
	v_fmac_f32_e32 v83, v18, v85
	v_fmac_f32_e32 v79, v24, v80
	v_fmac_f32_e32 v75, v27, v74
	v_add_f32_e32 v82, v34, v83
	v_fmac_f32_e32 v79, v22, v81
	v_fmac_f32_e32 v75, v28, v76
	v_fmac_f32_e32 v71, v30, v70
	v_add_f32_e32 v78, v82, v79
	v_fmac_f32_e32 v75, v26, v77
	v_fmac_f32_e32 v71, v31, v72
	v_add_f32_e32 v74, v78, v75
	v_fmac_f32_e32 v71, v29, v73
	v_add_f32_e32 v70, v74, v71
	v_min_f32_e32 v71, 0, v70
	v_mul_f32_e64 v70, |v70|, s59
	v_exp_f32_e32 v70, v70
	s_nop 0
	v_add_f32_e32 v70, 1.0, v70
	v_log_f32_e32 v70, v70
	s_nop 0
	v_mul_f32_e32 v72, 0x3f317217, v70
	v_fma_f32 v72, v70, s87, -v72
	v_fmac_f32_e32 v72, 0x3377d1cf, v70
	v_fmac_f32_e32 v72, 0x3f317217, v70
	v_sub_f32_e32 v70, v71, v72
	v_fmamk_f32 v226, v70, 0x3d800000, v225
	global_load_dwordx4 v[70:73], v67, s[98:99] offset:1104
	global_load_dwordx4 v[74:77], v67, s[98:99] offset:1088
	global_load_dwordx4 v[78:81], v67, s[98:99] offset:1072
	global_load_dwordx4 v[82:85], v67, s[98:99] offset:1056
	s_waitcnt vmcnt(7)
	v_mul_f32_e32 v1, v33, v1
	s_waitcnt vmcnt(6)
	v_mul_f32_e32 v5, v32, v5
	s_waitcnt vmcnt(5)
	v_mul_f32_e32 v9, v25, v9
	s_waitcnt vmcnt(4)
	v_mul_f32_e32 v13, v21, v13
	v_fmac_f32_e32 v13, v19, v12
	v_fmac_f32_e32 v13, v20, v14
	v_fmac_f32_e32 v9, v23, v8
	v_fmac_f32_e32 v13, v18, v15
	v_fmac_f32_e32 v9, v24, v10
	v_fmac_f32_e32 v5, v27, v4
	v_add_f32_e32 v12, v34, v13
	v_fmac_f32_e32 v9, v22, v11
	v_fmac_f32_e32 v5, v28, v6
	v_fmac_f32_e32 v1, v30, v0
	v_add_f32_e32 v8, v12, v9
	v_fmac_f32_e32 v5, v26, v7
	v_fmac_f32_e32 v1, v31, v2
	v_add_f32_e32 v4, v8, v5
	v_fmac_f32_e32 v1, v29, v3
	v_add_f32_e32 v0, v4, v1
	v_min_f32_e32 v1, 0, v0
	v_mul_f32_e64 v0, |v0|, s59
	v_exp_f32_e32 v0, v0
	s_nop 0
	v_add_f32_e32 v0, 1.0, v0
	v_log_f32_e32 v0, v0
	s_nop 0
	v_mul_f32_e32 v2, 0x3f317217, v0
	v_fma_f32 v2, v0, s87, -v2
	v_fmac_f32_e32 v2, 0x3377d1cf, v0
	v_fmac_f32_e32 v2, 0x3f317217, v0
	v_sub_f32_e32 v0, v1, v2
	v_fmamk_f32 v227, v0, 0x3d800000, v226
	global_load_dwordx4 v[0:3], v67, s[98:99] offset:1232
	global_load_dwordx4 v[4:7], v67, s[98:99] offset:1216
	global_load_dwordx4 v[8:11], v67, s[98:99] offset:1200
	global_load_dwordx4 v[12:15], v67, s[98:99] offset:1184
	s_waitcnt vmcnt(7)
	v_mul_f32_e32 v71, v33, v71
	s_waitcnt vmcnt(6)
	v_mul_f32_e32 v75, v32, v75
	s_waitcnt vmcnt(5)
	v_mul_f32_e32 v79, v25, v79
	s_waitcnt vmcnt(4)
	v_mul_f32_e32 v83, v21, v83
	v_fmac_f32_e32 v83, v19, v82
	v_fmac_f32_e32 v83, v20, v84
	v_fmac_f32_e32 v79, v23, v78
	v_fmac_f32_e32 v83, v18, v85
	v_fmac_f32_e32 v79, v24, v80
	v_fmac_f32_e32 v75, v27, v74
	v_add_f32_e32 v82, v34, v83
	v_fmac_f32_e32 v79, v22, v81
	v_fmac_f32_e32 v75, v28, v76
	v_fmac_f32_e32 v71, v30, v70
	v_add_f32_e32 v78, v82, v79
	v_fmac_f32_e32 v75, v26, v77
	v_fmac_f32_e32 v71, v31, v72
	v_add_f32_e32 v74, v78, v75
	v_fmac_f32_e32 v71, v29, v73
	v_add_f32_e32 v70, v74, v71
	v_min_f32_e32 v71, 0, v70
	v_mul_f32_e64 v70, |v70|, s59
	v_exp_f32_e32 v70, v70
	s_nop 0
	v_add_f32_e32 v70, 1.0, v70
	v_log_f32_e32 v70, v70
	s_nop 0
	v_mul_f32_e32 v72, 0x3f317217, v70
	v_fma_f32 v72, v70, s87, -v72
	v_fmac_f32_e32 v72, 0x3377d1cf, v70
	v_fmac_f32_e32 v72, 0x3f317217, v70
	v_sub_f32_e32 v70, v71, v72
	v_fmamk_f32 v228, v70, 0x3d800000, v227
	global_load_dwordx4 v[70:73], v67, s[98:99] offset:1360
	global_load_dwordx4 v[74:77], v67, s[98:99] offset:1344
	global_load_dwordx4 v[78:81], v67, s[98:99] offset:1328
	global_load_dwordx4 v[82:85], v67, s[98:99] offset:1312
	s_waitcnt vmcnt(7)
	v_mul_f32_e32 v1, v33, v1
	s_waitcnt vmcnt(6)
	v_mul_f32_e32 v5, v32, v5
	s_waitcnt vmcnt(5)
	v_mul_f32_e32 v9, v25, v9
	s_waitcnt vmcnt(4)
	v_mul_f32_e32 v13, v21, v13
	v_fmac_f32_e32 v13, v19, v12
	v_fmac_f32_e32 v13, v20, v14
	v_fmac_f32_e32 v9, v23, v8
	v_fmac_f32_e32 v13, v18, v15
	v_fmac_f32_e32 v9, v24, v10
	v_fmac_f32_e32 v5, v27, v4
	v_add_f32_e32 v12, v34, v13
	v_fmac_f32_e32 v9, v22, v11
	v_fmac_f32_e32 v5, v28, v6
	v_fmac_f32_e32 v1, v30, v0
	v_add_f32_e32 v8, v12, v9
	v_fmac_f32_e32 v5, v26, v7
	v_fmac_f32_e32 v1, v31, v2
	v_add_f32_e32 v4, v8, v5
	v_fmac_f32_e32 v1, v29, v3
	v_add_f32_e32 v0, v4, v1
	v_min_f32_e32 v1, 0, v0
	v_mul_f32_e64 v0, |v0|, s59
	v_exp_f32_e32 v0, v0
	s_nop 0
	v_add_f32_e32 v0, 1.0, v0
	v_log_f32_e32 v0, v0
	s_nop 0
	v_mul_f32_e32 v2, 0x3f317217, v0
	v_fma_f32 v2, v0, s87, -v2
	v_fmac_f32_e32 v2, 0x3377d1cf, v0
	v_fmac_f32_e32 v2, 0x3f317217, v0
	v_sub_f32_e32 v0, v1, v2
	v_fmamk_f32 v229, v0, 0x3d800000, v228
	global_load_dwordx4 v[0:3], v67, s[98:99] offset:1488
	global_load_dwordx4 v[4:7], v67, s[98:99] offset:1472
	global_load_dwordx4 v[8:11], v67, s[98:99] offset:1456
	global_load_dwordx4 v[12:15], v67, s[98:99] offset:1440
	s_waitcnt vmcnt(7)
	v_mul_f32_e32 v71, v33, v71
	s_waitcnt vmcnt(6)
	v_mul_f32_e32 v75, v32, v75
	s_waitcnt vmcnt(5)
	v_mul_f32_e32 v79, v25, v79
	s_waitcnt vmcnt(4)
; DI float logsig_fast(float z) { return fminf(z, 0.f) - __logf(1.0f + __expf(-fabsf(z))); }
; DI void p2_unit(int chunk, const Params& p, LAS unsigned char* lds) {
;     ...
;       for (int j2 = 0; j2 < 32; ++j2) { const f32x4* ar = (const f32x4*)(aux + (size_t)(tok0 + t0u + j2) * 32 + 8);
;           float z = bgc;
; #pragma unroll
;           for (int r4 = 0; r4 < 4; ++r4) { const f32x4 a = ar[r4]; z += a.x * w2c[4 * r4] + a.y * w2c[4 * r4 + 1] + a.z * w2c[4 * r4 + 2] + a.w * w2c[4 * r4 + 3]; }
;           bc += logsig_fast(z) * (1.0f / 16.0f); lc[j2] = bc; }
	v_mul_f32_e32 v83, v21, v83
	v_fmac_f32_e32 v83, v19, v82
	v_fmac_f32_e32 v83, v20, v84
	v_fmac_f32_e32 v79, v23, v78
	v_fmac_f32_e32 v83, v18, v85
	v_fmac_f32_e32 v79, v24, v80
	v_fmac_f32_e32 v75, v27, v74
	v_add_f32_e32 v82, v34, v83
	v_fmac_f32_e32 v79, v22, v81
	v_fmac_f32_e32 v75, v28, v76
	v_fmac_f32_e32 v71, v30, v70
	v_add_f32_e32 v78, v82, v79
	v_fmac_f32_e32 v75, v26, v77
	v_fmac_f32_e32 v71, v31, v72
	v_add_f32_e32 v74, v78, v75
	v_fmac_f32_e32 v71, v29, v73
	v_add_f32_e32 v70, v74, v71
	v_min_f32_e32 v71, 0, v70
	v_mul_f32_e64 v70, |v70|, s59
	v_exp_f32_e32 v70, v70
	s_nop 0
	v_add_f32_e32 v70, 1.0, v70
	v_log_f32_e32 v70, v70
	s_nop 0
	v_mul_f32_e32 v72, 0x3f317217, v70
	v_fma_f32 v72, v70, s87, -v72
	v_fmac_f32_e32 v72, 0x3377d1cf, v70
	v_fmac_f32_e32 v72, 0x3f317217, v70
	v_sub_f32_e32 v70, v71, v72
	v_fmamk_f32 v230, v70, 0x3d800000, v229
	global_load_dwordx4 v[70:73], v67, s[98:99] offset:1616
	global_load_dwordx4 v[74:77], v67, s[98:99] offset:1600
	global_load_dwordx4 v[78:81], v67, s[98:99] offset:1584
	global_load_dwordx4 v[82:85], v67, s[98:99] offset:1568
	s_waitcnt vmcnt(7)
	v_mul_f32_e32 v1, v33, v1
	s_waitcnt vmcnt(6)
	v_mul_f32_e32 v5, v32, v5
	s_waitcnt vmcnt(5)
	v_mul_f32_e32 v9, v25, v9
	s_waitcnt vmcnt(4)
	v_mul_f32_e32 v13, v21, v13
	v_fmac_f32_e32 v13, v19, v12
	v_fmac_f32_e32 v13, v20, v14
	v_fmac_f32_e32 v9, v23, v8
	v_fmac_f32_e32 v13, v18, v15
	v_fmac_f32_e32 v9, v24, v10
	v_fmac_f32_e32 v5, v27, v4
	v_add_f32_e32 v12, v34, v13
	v_fmac_f32_e32 v9, v22, v11
	v_fmac_f32_e32 v5, v28, v6
	v_fmac_f32_e32 v1, v30, v0
	v_add_f32_e32 v8, v12, v9
	v_fmac_f32_e32 v5, v26, v7
	v_fmac_f32_e32 v1, v31, v2
	v_add_f32_e32 v4, v8, v5
	v_fmac_f32_e32 v1, v29, v3
	v_add_f32_e32 v0, v4, v1
	v_min_f32_e32 v1, 0, v0
	v_mul_f32_e64 v0, |v0|, s59
	v_exp_f32_e32 v0, v0
	s_nop 0
	v_add_f32_e32 v0, 1.0, v0
	v_log_f32_e32 v0, v0
	s_nop 0
	v_mul_f32_e32 v2, 0x3f317217, v0
	v_fma_f32 v2, v0, s87, -v2
	v_fmac_f32_e32 v2, 0x3377d1cf, v0
	v_fmac_f32_e32 v2, 0x3f317217, v0
	v_sub_f32_e32 v0, v1, v2
	v_fmamk_f32 v231, v0, 0x3d800000, v230
	global_load_dwordx4 v[0:3], v67, s[98:99] offset:1744
	global_load_dwordx4 v[4:7], v67, s[98:99] offset:1728
	global_load_dwordx4 v[8:11], v67, s[98:99] offset:1712
	global_load_dwordx4 v[12:15], v67, s[98:99] offset:1696
	s_waitcnt vmcnt(7)
	v_mul_f32_e32 v71, v33, v71
	s_waitcnt vmcnt(6)
	v_mul_f32_e32 v75, v32, v75
	s_waitcnt vmcnt(5)
	v_mul_f32_e32 v79, v25, v79
	s_waitcnt vmcnt(4)
	v_mul_f32_e32 v83, v21, v83
	v_fmac_f32_e32 v83, v19, v82
	v_fmac_f32_e32 v83, v20, v84
	v_fmac_f32_e32 v79, v23, v78
	v_fmac_f32_e32 v83, v18, v85
	v_fmac_f32_e32 v79, v24, v80
	v_fmac_f32_e32 v75, v27, v74
	v_add_f32_e32 v82, v34, v83
	v_fmac_f32_e32 v79, v22, v81
	v_fmac_f32_e32 v75, v28, v76
	v_fmac_f32_e32 v71, v30, v70
	v_add_f32_e32 v78, v82, v79
	v_fmac_f32_e32 v75, v26, v77
	v_fmac_f32_e32 v71, v31, v72
	v_add_f32_e32 v74, v78, v75
	v_fmac_f32_e32 v71, v29, v73
	v_add_f32_e32 v70, v74, v71
	v_min_f32_e32 v71, 0, v70
	v_mul_f32_e64 v70, |v70|, s59
	v_exp_f32_e32 v70, v70
	s_nop 0
	v_add_f32_e32 v70, 1.0, v70
	v_log_f32_e32 v70, v70
	s_nop 0
	v_mul_f32_e32 v72, 0x3f317217, v70
	v_fma_f32 v72, v70, s87, -v72
	v_fmac_f32_e32 v72, 0x3377d1cf, v70
	v_fmac_f32_e32 v72, 0x3f317217, v70
	v_sub_f32_e32 v70, v71, v72
	v_fmamk_f32 v232, v70, 0x3d800000, v231
	global_load_dwordx4 v[70:73], v67, s[98:99] offset:1872
	global_load_dwordx4 v[74:77], v67, s[98:99] offset:1856
	global_load_dwordx4 v[78:81], v67, s[98:99] offset:1840
	global_load_dwordx4 v[82:85], v67, s[98:99] offset:1824
	s_waitcnt vmcnt(7)
	v_mul_f32_e32 v1, v33, v1
	s_waitcnt vmcnt(6)
	v_mul_f32_e32 v5, v32, v5
	s_waitcnt vmcnt(5)
	v_mul_f32_e32 v9, v25, v9
	s_waitcnt vmcnt(4)
	v_mul_f32_e32 v13, v21, v13
	v_fmac_f32_e32 v13, v19, v12
	v_fmac_f32_e32 v13, v20, v14
	v_fmac_f32_e32 v9, v23, v8
	v_fmac_f32_e32 v13, v18, v15
	v_fmac_f32_e32 v9, v24, v10
	v_fmac_f32_e32 v5, v27, v4
	v_add_f32_e32 v12, v34, v13
	v_fmac_f32_e32 v9, v22, v11
	v_fmac_f32_e32 v5, v28, v6
	v_fmac_f32_e32 v1, v30, v0
	v_add_f32_e32 v8, v12, v9
	v_fmac_f32_e32 v5, v26, v7
	v_fmac_f32_e32 v1, v31, v2
	v_add_f32_e32 v4, v8, v5
	v_fmac_f32_e32 v1, v29, v3
	v_add_f32_e32 v0, v4, v1
	v_min_f32_e32 v1, 0, v0
	v_mul_f32_e64 v0, |v0|, s59
	v_exp_f32_e32 v0, v0
	s_nop 0
	v_add_f32_e32 v0, 1.0, v0
	v_log_f32_e32 v0, v0
	s_nop 0
	v_mul_f32_e32 v2, 0x3f317217, v0
	v_fma_f32 v2, v0, s87, -v2
	v_fmac_f32_e32 v2, 0x3377d1cf, v0
	v_fmac_f32_e32 v2, 0x3f317217, v0
	v_sub_f32_e32 v0, v1, v2
	v_fmamk_f32 v233, v0, 0x3d800000, v232
	global_load_dwordx4 v[0:3], v67, s[98:99] offset:2000
	global_load_dwordx4 v[4:7], v67, s[98:99] offset:1984
	global_load_dwordx4 v[8:11], v67, s[98:99] offset:1968
	global_load_dwordx4 v[12:15], v67, s[98:99] offset:1952
	s_waitcnt vmcnt(7)
	v_mul_f32_e32 v71, v33, v71
	s_waitcnt vmcnt(6)
	v_mul_f32_e32 v75, v32, v75
	s_waitcnt vmcnt(5)
	v_mul_f32_e32 v79, v25, v79
	s_waitcnt vmcnt(4)
	v_mul_f32_e32 v83, v21, v83
	v_fmac_f32_e32 v83, v19, v82
	v_fmac_f32_e32 v83, v20, v84
	v_fmac_f32_e32 v79, v23, v78
	v_fmac_f32_e32 v83, v18, v85
	v_fmac_f32_e32 v79, v24, v80
	v_fmac_f32_e32 v75, v27, v74
	v_add_f32_e32 v82, v34, v83
	v_fmac_f32_e32 v79, v22, v81
	v_fmac_f32_e32 v75, v28, v76
	v_fmac_f32_e32 v71, v30, v70
	v_add_f32_e32 v78, v82, v79
	v_fmac_f32_e32 v75, v26, v77
	v_fmac_f32_e32 v71, v31, v72
	v_add_f32_e32 v74, v78, v75
	v_fmac_f32_e32 v71, v29, v73
	v_add_f32_e32 v70, v74, v71
	v_min_f32_e32 v71, 0, v70
	v_mul_f32_e64 v70, |v70|, s59
	v_exp_f32_e32 v70, v70
	s_nop 0
	v_add_f32_e32 v70, 1.0, v70
	v_log_f32_e32 v70, v70
	s_nop 0
	v_mul_f32_e32 v72, 0x3f317217, v70
	v_fma_f32 v72, v70, s87, -v72
	v_fmac_f32_e32 v72, 0x3377d1cf, v70
	v_fmac_f32_e32 v72, 0x3f317217, v70
	v_sub_f32_e32 v70, v71, v72
	v_fmamk_f32 v234, v70, 0x3d800000, v233
	global_load_dwordx4 v[70:73], v67, s[98:99] offset:2128
	global_load_dwordx4 v[74:77], v67, s[98:99] offset:2112
	global_load_dwordx4 v[78:81], v67, s[98:99] offset:2096
	global_load_dwordx4 v[82:85], v67, s[98:99] offset:2080
	s_waitcnt vmcnt(7)
; DI float logsig_fast(float z) { return fminf(z, 0.f) - __logf(1.0f + __expf(-fabsf(z))); }
; DI void p2_unit(int chunk, const Params& p, LAS unsigned char* lds) {
;     ...
;       for (int j2 = 0; j2 < 32; ++j2) { const f32x4* ar = (const f32x4*)(aux + (size_t)(tok0 + t0u + j2) * 32 + 8);
;           float z = bgc;
; #pragma unroll
;           for (int r4 = 0; r4 < 4; ++r4) { const f32x4 a = ar[r4]; z += a.x * w2c[4 * r4] + a.y * w2c[4 * r4 + 1] + a.z * w2c[4 * r4 + 2] + a.w * w2c[4 * r4 + 3]; }
;           bc += logsig_fast(z) * (1.0f / 16.0f); lc[j2] = bc; }
	v_mul_f32_e32 v1, v33, v1
	s_waitcnt vmcnt(6)
	v_mul_f32_e32 v5, v32, v5
	s_waitcnt vmcnt(5)
	v_mul_f32_e32 v9, v25, v9
	s_waitcnt vmcnt(4)
	v_mul_f32_e32 v13, v21, v13
	v_fmac_f32_e32 v13, v19, v12
	v_fmac_f32_e32 v13, v20, v14
	v_fmac_f32_e32 v9, v23, v8
	v_fmac_f32_e32 v13, v18, v15
	v_fmac_f32_e32 v9, v24, v10
	v_fmac_f32_e32 v5, v27, v4
	v_add_f32_e32 v12, v34, v13
	v_fmac_f32_e32 v9, v22, v11
	v_fmac_f32_e32 v5, v28, v6
	v_fmac_f32_e32 v1, v30, v0
	v_add_f32_e32 v8, v12, v9
	v_fmac_f32_e32 v5, v26, v7
	v_fmac_f32_e32 v1, v31, v2
	v_add_f32_e32 v4, v8, v5
	v_fmac_f32_e32 v1, v29, v3
	v_add_f32_e32 v0, v4, v1
	v_min_f32_e32 v1, 0, v0
	v_mul_f32_e64 v0, |v0|, s59
	v_exp_f32_e32 v0, v0
	s_nop 0
	v_add_f32_e32 v0, 1.0, v0
	v_log_f32_e32 v0, v0
	s_nop 0
	v_mul_f32_e32 v2, 0x3f317217, v0
	v_fma_f32 v2, v0, s87, -v2
	v_fmac_f32_e32 v2, 0x3377d1cf, v0
	v_fmac_f32_e32 v2, 0x3f317217, v0
	v_sub_f32_e32 v0, v1, v2
	v_fmamk_f32 v235, v0, 0x3d800000, v234
	global_load_dwordx4 v[0:3], v67, s[98:99] offset:2256
	global_load_dwordx4 v[4:7], v67, s[98:99] offset:2240
	global_load_dwordx4 v[8:11], v67, s[98:99] offset:2224
	global_load_dwordx4 v[12:15], v67, s[98:99] offset:2208
	s_waitcnt vmcnt(7)
	v_mul_f32_e32 v71, v33, v71
	s_waitcnt vmcnt(6)
	v_mul_f32_e32 v75, v32, v75
	s_waitcnt vmcnt(5)
	v_mul_f32_e32 v79, v25, v79
	s_waitcnt vmcnt(4)
	v_mul_f32_e32 v83, v21, v83
	v_fmac_f32_e32 v83, v19, v82
	v_fmac_f32_e32 v83, v20, v84
	v_fmac_f32_e32 v79, v23, v78
	v_fmac_f32_e32 v83, v18, v85
	v_fmac_f32_e32 v79, v24, v80
	v_fmac_f32_e32 v75, v27, v74
	v_add_f32_e32 v82, v34, v83
	v_fmac_f32_e32 v79, v22, v81
	v_fmac_f32_e32 v75, v28, v76
	v_fmac_f32_e32 v71, v30, v70
	v_add_f32_e32 v78, v82, v79
	v_fmac_f32_e32 v75, v26, v77
	v_fmac_f32_e32 v71, v31, v72
	v_add_f32_e32 v74, v78, v75
	v_fmac_f32_e32 v71, v29, v73
	v_add_f32_e32 v70, v74, v71
	v_min_f32_e32 v71, 0, v70
	v_mul_f32_e64 v70, |v70|, s59
	v_exp_f32_e32 v70, v70
	s_nop 0
	v_add_f32_e32 v70, 1.0, v70
	v_log_f32_e32 v70, v70
	s_nop 0
	v_mul_f32_e32 v72, 0x3f317217, v70
	v_fma_f32 v72, v70, s87, -v72
	v_fmac_f32_e32 v72, 0x3377d1cf, v70
	v_fmac_f32_e32 v72, 0x3f317217, v70
	v_sub_f32_e32 v70, v71, v72
	v_fmamk_f32 v236, v70, 0x3d800000, v235
	global_load_dwordx4 v[70:73], v67, s[98:99] offset:2384
	global_load_dwordx4 v[74:77], v67, s[98:99] offset:2368
	global_load_dwordx4 v[78:81], v67, s[98:99] offset:2352
	global_load_dwordx4 v[82:85], v67, s[98:99] offset:2336
	s_waitcnt vmcnt(7)
	v_mul_f32_e32 v1, v33, v1
	s_waitcnt vmcnt(6)
	v_mul_f32_e32 v5, v32, v5
	s_waitcnt vmcnt(5)
	v_mul_f32_e32 v9, v25, v9
	s_waitcnt vmcnt(4)
	v_mul_f32_e32 v13, v21, v13
	v_fmac_f32_e32 v13, v19, v12
	v_fmac_f32_e32 v13, v20, v14
	v_fmac_f32_e32 v9, v23, v8
	v_fmac_f32_e32 v13, v18, v15
	v_fmac_f32_e32 v9, v24, v10
	v_fmac_f32_e32 v5, v27, v4
	v_add_f32_e32 v12, v34, v13
	v_fmac_f32_e32 v9, v22, v11
	v_fmac_f32_e32 v5, v28, v6
	v_fmac_f32_e32 v1, v30, v0
	v_add_f32_e32 v8, v12, v9
	v_fmac_f32_e32 v5, v26, v7
	v_fmac_f32_e32 v1, v31, v2
	v_add_f32_e32 v4, v8, v5
	v_fmac_f32_e32 v1, v29, v3
	v_add_f32_e32 v0, v4, v1
	v_min_f32_e32 v1, 0, v0
	v_mul_f32_e64 v0, |v0|, s59
	v_exp_f32_e32 v0, v0
	s_nop 0
	v_add_f32_e32 v0, 1.0, v0
	v_log_f32_e32 v0, v0
	s_nop 0
	v_mul_f32_e32 v2, 0x3f317217, v0
	v_fma_f32 v2, v0, s87, -v2
	v_fmac_f32_e32 v2, 0x3377d1cf, v0
	v_fmac_f32_e32 v2, 0x3f317217, v0
	v_sub_f32_e32 v0, v1, v2
	v_fmamk_f32 v237, v0, 0x3d800000, v236
	global_load_dwordx4 v[0:3], v67, s[98:99] offset:2512
	global_load_dwordx4 v[4:7], v67, s[98:99] offset:2496
	global_load_dwordx4 v[8:11], v67, s[98:99] offset:2480
	global_load_dwordx4 v[12:15], v67, s[98:99] offset:2464
	s_waitcnt vmcnt(7)
	v_mul_f32_e32 v71, v33, v71
	s_waitcnt vmcnt(6)
	v_mul_f32_e32 v75, v32, v75
	s_waitcnt vmcnt(5)
	v_mul_f32_e32 v79, v25, v79
	s_waitcnt vmcnt(4)
	v_mul_f32_e32 v83, v21, v83
	v_fmac_f32_e32 v83, v19, v82
	v_fmac_f32_e32 v83, v20, v84
	v_fmac_f32_e32 v79, v23, v78
	v_fmac_f32_e32 v83, v18, v85
	v_fmac_f32_e32 v79, v24, v80
	v_fmac_f32_e32 v75, v27, v74
	v_add_f32_e32 v82, v34, v83
	v_fmac_f32_e32 v79, v22, v81
	v_fmac_f32_e32 v75, v28, v76
	v_fmac_f32_e32 v71, v30, v70
	v_add_f32_e32 v78, v82, v79
	v_fmac_f32_e32 v75, v26, v77
	v_fmac_f32_e32 v71, v31, v72
	v_add_f32_e32 v74, v78, v75
	v_fmac_f32_e32 v71, v29, v73
	v_add_f32_e32 v70, v74, v71
	v_min_f32_e32 v71, 0, v70
	v_mul_f32_e64 v70, |v70|, s59
	v_exp_f32_e32 v70, v70
	s_nop 0
	v_add_f32_e32 v70, 1.0, v70
	v_log_f32_e32 v70, v70
	s_nop 0
	v_mul_f32_e32 v72, 0x3f317217, v70
	v_fma_f32 v72, v70, s87, -v72
	v_fmac_f32_e32 v72, 0x3377d1cf, v70
	v_fmac_f32_e32 v72, 0x3f317217, v70
	v_sub_f32_e32 v70, v71, v72
	v_fmamk_f32 v238, v70, 0x3d800000, v237
	global_load_dwordx4 v[70:73], v67, s[98:99] offset:2640
	global_load_dwordx4 v[74:77], v67, s[98:99] offset:2624
	global_load_dwordx4 v[78:81], v67, s[98:99] offset:2608
	global_load_dwordx4 v[82:85], v67, s[98:99] offset:2592
	s_waitcnt vmcnt(7)
	v_mul_f32_e32 v1, v33, v1
	s_waitcnt vmcnt(6)
	v_mul_f32_e32 v5, v32, v5
	s_waitcnt vmcnt(5)
	v_mul_f32_e32 v9, v25, v9
	s_waitcnt vmcnt(4)
	v_mul_f32_e32 v13, v21, v13
	v_fmac_f32_e32 v13, v19, v12
	v_fmac_f32_e32 v13, v20, v14
	v_fmac_f32_e32 v9, v23, v8
	v_fmac_f32_e32 v13, v18, v15
	v_fmac_f32_e32 v9, v24, v10
	v_fmac_f32_e32 v5, v27, v4
	v_add_f32_e32 v12, v34, v13
	v_fmac_f32_e32 v9, v22, v11
	v_fmac_f32_e32 v5, v28, v6
	v_fmac_f32_e32 v1, v30, v0
	v_add_f32_e32 v8, v12, v9
	v_fmac_f32_e32 v5, v26, v7
	v_fmac_f32_e32 v1, v31, v2
	v_add_f32_e32 v4, v8, v5
	v_fmac_f32_e32 v1, v29, v3
	v_add_f32_e32 v0, v4, v1
	v_min_f32_e32 v1, 0, v0
	v_mul_f32_e64 v0, |v0|, s59
	v_exp_f32_e32 v0, v0
	s_nop 0
	v_add_f32_e32 v0, 1.0, v0
	v_log_f32_e32 v0, v0
	s_nop 0
	v_mul_f32_e32 v2, 0x3f317217, v0
	v_fma_f32 v2, v0, s87, -v2
	v_fmac_f32_e32 v2, 0x3377d1cf, v0
	v_fmac_f32_e32 v2, 0x3f317217, v0
	v_sub_f32_e32 v0, v1, v2
	v_fmamk_f32 v239, v0, 0x3d800000, v238
	global_load_dwordx4 v[0:3], v67, s[98:99] offset:2768
	global_load_dwordx4 v[4:7], v67, s[98:99] offset:2752
	global_load_dwordx4 v[8:11], v67, s[98:99] offset:2736
	global_load_dwordx4 v[12:15], v67, s[98:99] offset:2720
	s_waitcnt vmcnt(7)
; DI float logsig_fast(float z) { return fminf(z, 0.f) - __logf(1.0f + __expf(-fabsf(z))); }
; DI void p2_unit(int chunk, const Params& p, LAS unsigned char* lds) {
;     ...
;       for (int j2 = 0; j2 < 32; ++j2) { const f32x4* ar = (const f32x4*)(aux + (size_t)(tok0 + t0u + j2) * 32 + 8);
;           float z = bgc;
; #pragma unroll
;           for (int r4 = 0; r4 < 4; ++r4) { const f32x4 a = ar[r4]; z += a.x * w2c[4 * r4] + a.y * w2c[4 * r4 + 1] + a.z * w2c[4 * r4 + 2] + a.w * w2c[4 * r4 + 3]; }
;           bc += logsig_fast(z) * (1.0f / 16.0f); lc[j2] = bc; }
	v_mul_f32_e32 v71, v33, v71
	s_waitcnt vmcnt(6)
	v_mul_f32_e32 v75, v32, v75
	s_waitcnt vmcnt(5)
	v_mul_f32_e32 v79, v25, v79
	s_waitcnt vmcnt(4)
	v_mul_f32_e32 v83, v21, v83
	v_fmac_f32_e32 v83, v19, v82
	v_fmac_f32_e32 v83, v20, v84
	v_fmac_f32_e32 v79, v23, v78
	v_fmac_f32_e32 v83, v18, v85
	v_fmac_f32_e32 v79, v24, v80
	v_fmac_f32_e32 v75, v27, v74
	v_add_f32_e32 v82, v34, v83
	v_fmac_f32_e32 v79, v22, v81
	v_fmac_f32_e32 v75, v28, v76
	v_fmac_f32_e32 v71, v30, v70
	v_add_f32_e32 v78, v82, v79
	v_fmac_f32_e32 v75, v26, v77
	v_fmac_f32_e32 v71, v31, v72
	v_add_f32_e32 v74, v78, v75
	v_fmac_f32_e32 v71, v29, v73
	v_add_f32_e32 v70, v74, v71
	v_min_f32_e32 v71, 0, v70
	v_mul_f32_e64 v70, |v70|, s59
	v_exp_f32_e32 v70, v70
	s_nop 0
	v_add_f32_e32 v70, 1.0, v70
	v_log_f32_e32 v70, v70
	s_nop 0
	v_mul_f32_e32 v72, 0x3f317217, v70
	v_fma_f32 v72, v70, s87, -v72
	v_fmac_f32_e32 v72, 0x3377d1cf, v70
	v_fmac_f32_e32 v72, 0x3f317217, v70
	v_sub_f32_e32 v70, v71, v72
	v_fmamk_f32 v240, v70, 0x3d800000, v239
	global_load_dwordx4 v[70:73], v67, s[98:99] offset:2896
	global_load_dwordx4 v[74:77], v67, s[98:99] offset:2880
	global_load_dwordx4 v[78:81], v67, s[98:99] offset:2864
	global_load_dwordx4 v[82:85], v67, s[98:99] offset:2848
	s_waitcnt vmcnt(7)
	v_mul_f32_e32 v1, v33, v1
	s_waitcnt vmcnt(6)
	v_mul_f32_e32 v5, v32, v5
	s_waitcnt vmcnt(5)
	v_mul_f32_e32 v9, v25, v9
	s_waitcnt vmcnt(4)
	v_mul_f32_e32 v13, v21, v13
	v_fmac_f32_e32 v13, v19, v12
	v_fmac_f32_e32 v13, v20, v14
	v_fmac_f32_e32 v9, v23, v8
	v_fmac_f32_e32 v13, v18, v15
	v_fmac_f32_e32 v9, v24, v10
	v_fmac_f32_e32 v5, v27, v4
	v_add_f32_e32 v12, v34, v13
	v_fmac_f32_e32 v9, v22, v11
	v_fmac_f32_e32 v5, v28, v6
	v_fmac_f32_e32 v1, v30, v0
	v_add_f32_e32 v8, v12, v9
	v_fmac_f32_e32 v5, v26, v7
	v_fmac_f32_e32 v1, v31, v2
	v_add_f32_e32 v4, v8, v5
	v_fmac_f32_e32 v1, v29, v3
	v_add_f32_e32 v0, v4, v1
	v_min_f32_e32 v1, 0, v0
	v_mul_f32_e64 v0, |v0|, s59
	v_exp_f32_e32 v0, v0
	s_nop 0
	v_add_f32_e32 v0, 1.0, v0
	v_log_f32_e32 v0, v0
	s_nop 0
	v_mul_f32_e32 v2, 0x3f317217, v0
	v_fma_f32 v2, v0, s87, -v2
	v_fmac_f32_e32 v2, 0x3377d1cf, v0
	v_fmac_f32_e32 v2, 0x3f317217, v0
	v_sub_f32_e32 v0, v1, v2
	v_fmamk_f32 v241, v0, 0x3d800000, v240
	global_load_dwordx4 v[0:3], v67, s[98:99] offset:3024
	global_load_dwordx4 v[4:7], v67, s[98:99] offset:3008
	global_load_dwordx4 v[8:11], v67, s[98:99] offset:2992
	global_load_dwordx4 v[12:15], v67, s[98:99] offset:2976
	s_waitcnt vmcnt(7)
	v_mul_f32_e32 v71, v33, v71
	s_waitcnt vmcnt(6)
	v_mul_f32_e32 v75, v32, v75
	s_waitcnt vmcnt(5)
	v_mul_f32_e32 v79, v25, v79
	s_waitcnt vmcnt(4)
	v_mul_f32_e32 v83, v21, v83
	v_fmac_f32_e32 v83, v19, v82
	v_fmac_f32_e32 v83, v20, v84
	v_fmac_f32_e32 v79, v23, v78
	v_fmac_f32_e32 v83, v18, v85
	v_fmac_f32_e32 v79, v24, v80
	v_fmac_f32_e32 v75, v27, v74
	v_add_f32_e32 v82, v34, v83
	v_fmac_f32_e32 v79, v22, v81
	v_fmac_f32_e32 v75, v28, v76
	v_fmac_f32_e32 v71, v30, v70
	v_add_f32_e32 v78, v82, v79
	v_fmac_f32_e32 v75, v26, v77
	v_fmac_f32_e32 v71, v31, v72
	v_add_f32_e32 v74, v78, v75
	v_fmac_f32_e32 v71, v29, v73
	v_add_f32_e32 v70, v74, v71
	v_min_f32_e32 v71, 0, v70
	v_mul_f32_e64 v70, |v70|, s59
	v_exp_f32_e32 v70, v70
	s_nop 0
	v_add_f32_e32 v70, 1.0, v70
	v_log_f32_e32 v70, v70
	s_nop 0
	v_mul_f32_e32 v72, 0x3f317217, v70
	v_fma_f32 v72, v70, s87, -v72
	v_fmac_f32_e32 v72, 0x3377d1cf, v70
	v_fmac_f32_e32 v72, 0x3f317217, v70
	v_sub_f32_e32 v70, v71, v72
	v_fmamk_f32 v242, v70, 0x3d800000, v241
	global_load_dwordx4 v[70:73], v67, s[98:99] offset:3152
	global_load_dwordx4 v[74:77], v67, s[98:99] offset:3136
	global_load_dwordx4 v[78:81], v67, s[98:99] offset:3120
	global_load_dwordx4 v[82:85], v67, s[98:99] offset:3104
	s_waitcnt vmcnt(7)
	v_mul_f32_e32 v1, v33, v1
	s_waitcnt vmcnt(6)
	v_mul_f32_e32 v5, v32, v5
	s_waitcnt vmcnt(5)
	v_mul_f32_e32 v9, v25, v9
	s_waitcnt vmcnt(4)
	v_mul_f32_e32 v13, v21, v13
	v_fmac_f32_e32 v13, v19, v12
	v_fmac_f32_e32 v13, v20, v14
	v_fmac_f32_e32 v9, v23, v8
	v_fmac_f32_e32 v13, v18, v15
	v_fmac_f32_e32 v9, v24, v10
	v_fmac_f32_e32 v5, v27, v4
	v_add_f32_e32 v12, v34, v13
	v_fmac_f32_e32 v9, v22, v11
	v_fmac_f32_e32 v5, v28, v6
	v_fmac_f32_e32 v1, v30, v0
	v_add_f32_e32 v8, v12, v9
	v_fmac_f32_e32 v5, v26, v7
	v_fmac_f32_e32 v1, v31, v2
	v_add_f32_e32 v4, v8, v5
	v_fmac_f32_e32 v1, v29, v3
	v_add_f32_e32 v0, v4, v1
	v_min_f32_e32 v1, 0, v0
	v_mul_f32_e64 v0, |v0|, s59
	v_exp_f32_e32 v0, v0
	s_nop 0
	v_add_f32_e32 v0, 1.0, v0
	v_log_f32_e32 v0, v0
	s_nop 0
	v_mul_f32_e32 v2, 0x3f317217, v0
	v_fma_f32 v2, v0, s87, -v2
	v_fmac_f32_e32 v2, 0x3377d1cf, v0
	v_fmac_f32_e32 v2, 0x3f317217, v0
	v_sub_f32_e32 v0, v1, v2
	v_fmamk_f32 v243, v0, 0x3d800000, v242
	global_load_dwordx4 v[0:3], v67, s[98:99] offset:3280
	global_load_dwordx4 v[4:7], v67, s[98:99] offset:3264
	global_load_dwordx4 v[8:11], v67, s[98:99] offset:3248
	global_load_dwordx4 v[12:15], v67, s[98:99] offset:3232
	s_waitcnt vmcnt(7)
	v_mul_f32_e32 v71, v33, v71
	s_waitcnt vmcnt(6)
	v_mul_f32_e32 v75, v32, v75
	s_waitcnt vmcnt(5)
	v_mul_f32_e32 v79, v25, v79
	s_waitcnt vmcnt(4)
; DI float logsig_fast(float z) { return fminf(z, 0.f) - __logf(1.0f + __expf(-fabsf(z))); }
; DI void p2_unit(int chunk, const Params& p, LAS unsigned char* lds) {
;     ...
;       for (int j2 = 0; j2 < 32; ++j2) { const f32x4* ar = (const f32x4*)(aux + (size_t)(tok0 + t0u + j2) * 32 + 8);
;           float z = bgc;
; #pragma unroll
;           for (int r4 = 0; r4 < 4; ++r4) { const f32x4 a = ar[r4]; z += a.x * w2c[4 * r4] + a.y * w2c[4 * r4 + 1] + a.z * w2c[4 * r4 + 2] + a.w * w2c[4 * r4 + 3]; }
;           bc += logsig_fast(z) * (1.0f / 16.0f); lc[j2] = bc; }
	v_mul_f32_e32 v83, v21, v83
	v_fmac_f32_e32 v83, v19, v82
	v_fmac_f32_e32 v83, v20, v84
	v_fmac_f32_e32 v79, v23, v78
	v_fmac_f32_e32 v83, v18, v85
	v_fmac_f32_e32 v79, v24, v80
	v_fmac_f32_e32 v75, v27, v74
	v_add_f32_e32 v82, v34, v83
	v_fmac_f32_e32 v79, v22, v81
	v_fmac_f32_e32 v75, v28, v76
	v_fmac_f32_e32 v71, v30, v70
	v_add_f32_e32 v78, v82, v79
	v_fmac_f32_e32 v75, v26, v77
	v_fmac_f32_e32 v71, v31, v72
	v_add_f32_e32 v74, v78, v75
	v_fmac_f32_e32 v71, v29, v73
	v_add_f32_e32 v70, v74, v71
	v_min_f32_e32 v71, 0, v70
	v_mul_f32_e64 v70, |v70|, s59
	v_exp_f32_e32 v70, v70
	s_nop 0
	v_add_f32_e32 v70, 1.0, v70
	v_log_f32_e32 v70, v70
	s_nop 0
	v_mul_f32_e32 v72, 0x3f317217, v70
	v_fma_f32 v72, v70, s87, -v72
	v_fmac_f32_e32 v72, 0x3377d1cf, v70
	v_fmac_f32_e32 v72, 0x3f317217, v70
	v_sub_f32_e32 v70, v71, v72
	v_fmamk_f32 v244, v70, 0x3d800000, v243
	global_load_dwordx4 v[70:73], v67, s[98:99] offset:3408
	global_load_dwordx4 v[74:77], v67, s[98:99] offset:3392
	global_load_dwordx4 v[78:81], v67, s[98:99] offset:3376
	global_load_dwordx4 v[82:85], v67, s[98:99] offset:3360
	s_waitcnt vmcnt(7)
	v_mul_f32_e32 v1, v33, v1
	s_waitcnt vmcnt(6)
	v_mul_f32_e32 v5, v32, v5
	s_waitcnt vmcnt(5)
	v_mul_f32_e32 v9, v25, v9
	s_waitcnt vmcnt(4)
	v_mul_f32_e32 v13, v21, v13
	v_fmac_f32_e32 v13, v19, v12
	v_fmac_f32_e32 v13, v20, v14
	v_fmac_f32_e32 v9, v23, v8
	v_fmac_f32_e32 v13, v18, v15
	v_fmac_f32_e32 v9, v24, v10
	v_fmac_f32_e32 v5, v27, v4
	v_add_f32_e32 v12, v34, v13
	v_fmac_f32_e32 v9, v22, v11
	v_fmac_f32_e32 v5, v28, v6
	v_fmac_f32_e32 v1, v30, v0
	v_add_f32_e32 v8, v12, v9
	v_fmac_f32_e32 v5, v26, v7
	v_fmac_f32_e32 v1, v31, v2
	v_add_f32_e32 v4, v8, v5
	v_fmac_f32_e32 v1, v29, v3
	v_add_f32_e32 v0, v4, v1
	v_min_f32_e32 v1, 0, v0
	v_mul_f32_e64 v0, |v0|, s59
	v_exp_f32_e32 v0, v0
	s_nop 0
	v_add_f32_e32 v0, 1.0, v0
	v_log_f32_e32 v0, v0
	s_nop 0
	v_mul_f32_e32 v2, 0x3f317217, v0
	v_fma_f32 v2, v0, s87, -v2
	v_fmac_f32_e32 v2, 0x3377d1cf, v0
	v_fmac_f32_e32 v2, 0x3f317217, v0
	v_sub_f32_e32 v0, v1, v2
	v_fmamk_f32 v245, v0, 0x3d800000, v244
	global_load_dwordx4 v[0:3], v67, s[98:99] offset:3536
	global_load_dwordx4 v[4:7], v67, s[98:99] offset:3520
	global_load_dwordx4 v[8:11], v67, s[98:99] offset:3504
	global_load_dwordx4 v[12:15], v67, s[98:99] offset:3488
	s_waitcnt vmcnt(7)
	v_mul_f32_e32 v71, v33, v71
	s_waitcnt vmcnt(6)
	v_mul_f32_e32 v75, v32, v75
	s_waitcnt vmcnt(5)
	v_mul_f32_e32 v79, v25, v79
	s_waitcnt vmcnt(4)
	v_mul_f32_e32 v83, v21, v83
	v_fmac_f32_e32 v83, v19, v82
	v_fmac_f32_e32 v83, v20, v84
	v_fmac_f32_e32 v79, v23, v78
	v_fmac_f32_e32 v83, v18, v85
	v_fmac_f32_e32 v79, v24, v80
	v_fmac_f32_e32 v75, v27, v74
	v_add_f32_e32 v82, v34, v83
	v_fmac_f32_e32 v79, v22, v81
	v_fmac_f32_e32 v75, v28, v76
	v_fmac_f32_e32 v71, v30, v70
	v_add_f32_e32 v78, v82, v79
	v_fmac_f32_e32 v75, v26, v77
	v_fmac_f32_e32 v71, v31, v72
	v_add_f32_e32 v74, v78, v75
	v_fmac_f32_e32 v71, v29, v73
	v_add_f32_e32 v70, v74, v71
	v_min_f32_e32 v71, 0, v70
	v_mul_f32_e64 v70, |v70|, s59
	v_exp_f32_e32 v70, v70
	s_nop 0
	v_add_f32_e32 v70, 1.0, v70
	v_log_f32_e32 v70, v70
	s_nop 0
	v_mul_f32_e32 v72, 0x3f317217, v70
	v_fma_f32 v72, v70, s87, -v72
	v_fmac_f32_e32 v72, 0x3377d1cf, v70
	v_fmac_f32_e32 v72, 0x3f317217, v70
	v_sub_f32_e32 v70, v71, v72
	v_fmamk_f32 v246, v70, 0x3d800000, v245
	global_load_dwordx4 v[70:73], v67, s[98:99] offset:3664
	global_load_dwordx4 v[74:77], v67, s[98:99] offset:3648
	global_load_dwordx4 v[78:81], v67, s[98:99] offset:3632
	global_load_dwordx4 v[82:85], v67, s[98:99] offset:3616
	s_waitcnt vmcnt(7)
	v_mul_f32_e32 v1, v33, v1
	s_waitcnt vmcnt(6)
	v_mul_f32_e32 v5, v32, v5
	s_waitcnt vmcnt(5)
	v_mul_f32_e32 v9, v25, v9
	s_waitcnt vmcnt(4)
	v_mul_f32_e32 v13, v21, v13
	v_fmac_f32_e32 v13, v19, v12
	v_fmac_f32_e32 v13, v20, v14
	v_fmac_f32_e32 v9, v23, v8
	v_fmac_f32_e32 v13, v18, v15
	v_fmac_f32_e32 v9, v24, v10
	v_fmac_f32_e32 v5, v27, v4
	v_add_f32_e32 v12, v34, v13
	v_fmac_f32_e32 v9, v22, v11
	v_fmac_f32_e32 v5, v28, v6
	v_fmac_f32_e32 v1, v30, v0
	v_add_f32_e32 v8, v12, v9
	v_fmac_f32_e32 v5, v26, v7
	v_fmac_f32_e32 v1, v31, v2
	v_add_f32_e32 v4, v8, v5
	v_fmac_f32_e32 v1, v29, v3
	v_add_f32_e32 v0, v4, v1
	v_min_f32_e32 v1, 0, v0
	v_mul_f32_e64 v0, |v0|, s59
	v_exp_f32_e32 v0, v0
	s_nop 0
	v_add_f32_e32 v0, 1.0, v0
	v_log_f32_e32 v0, v0
	s_nop 0
	v_mul_f32_e32 v2, 0x3f317217, v0
	v_fma_f32 v2, v0, s87, -v2
	v_fmac_f32_e32 v2, 0x3377d1cf, v0
	v_fmac_f32_e32 v2, 0x3f317217, v0
	v_sub_f32_e32 v0, v1, v2
	v_fmamk_f32 v247, v0, 0x3d800000, v246
	global_load_dwordx4 v[0:3], v67, s[98:99] offset:3792
	global_load_dwordx4 v[4:7], v67, s[98:99] offset:3776
	global_load_dwordx4 v[8:11], v67, s[98:99] offset:3760
	global_load_dwordx4 v[12:15], v67, s[98:99] offset:3744
	s_waitcnt vmcnt(7)
	v_mul_f32_e32 v71, v33, v71
	s_waitcnt vmcnt(6)
	v_mul_f32_e32 v75, v32, v75
	s_waitcnt vmcnt(5)
	v_mul_f32_e32 v79, v25, v79
	s_waitcnt vmcnt(4)
	v_mul_f32_e32 v83, v21, v83
	v_fmac_f32_e32 v83, v19, v82
	v_fmac_f32_e32 v83, v20, v84
	v_fmac_f32_e32 v79, v23, v78
	v_fmac_f32_e32 v83, v18, v85
	v_fmac_f32_e32 v79, v24, v80
	v_fmac_f32_e32 v75, v27, v74
	v_add_f32_e32 v82, v34, v83
	v_fmac_f32_e32 v79, v22, v81
	v_fmac_f32_e32 v75, v28, v76
	v_fmac_f32_e32 v71, v30, v70
	v_add_f32_e32 v78, v82, v79
	v_fmac_f32_e32 v75, v26, v77
	v_fmac_f32_e32 v71, v31, v72
	v_add_f32_e32 v74, v78, v75
	v_fmac_f32_e32 v71, v29, v73
	v_add_f32_e32 v70, v74, v71
	v_min_f32_e32 v71, 0, v70
	v_mul_f32_e64 v70, |v70|, s59
	v_exp_f32_e32 v70, v70
	s_nop 0
	v_add_f32_e32 v70, 1.0, v70
	v_log_f32_e32 v70, v70
	s_nop 0
	v_mul_f32_e32 v72, 0x3f317217, v70
	v_fma_f32 v72, v70, s87, -v72
	v_fmac_f32_e32 v72, 0x3377d1cf, v70
	v_fmac_f32_e32 v72, 0x3f317217, v70
	v_sub_f32_e32 v70, v71, v72
	v_fmamk_f32 v248, v70, 0x3d800000, v247
	global_load_dwordx4 v[70:73], v67, s[98:99] offset:3920
	global_load_dwordx4 v[74:77], v67, s[98:99] offset:3904
	global_load_dwordx4 v[78:81], v67, s[98:99] offset:3888
	global_load_dwordx4 v[82:85], v67, s[98:99] offset:3872
	s_waitcnt vmcnt(7)
; DI bf16_t f2bf(float f) { return (bf16_t)(pk2(f, 0.f) & 0xffffu); }
; DI float logsig_fast(float z) { return fminf(z, 0.f) - __logf(1.0f + __expf(-fabsf(z))); }
; DI void p2_unit(int chunk, const Params& p, LAS unsigned char* lds) {
;     ...
;       for (int j2 = 0; j2 < 32; ++j2) { const f32x4* ar = (const f32x4*)(aux + (size_t)(tok0 + t0u + j2) * 32 + 8);
;           float z = bgc;
; #pragma unroll
;           for (int r4 = 0; r4 < 4; ++r4) { const f32x4 a = ar[r4]; z += a.x * w2c[4 * r4] + a.y * w2c[4 * r4 + 1] + a.z * w2c[4 * r4 + 2] + a.w * w2c[4 * r4 + 3]; }
;           bc += logsig_fast(z) * (1.0f / 16.0f); lc[j2] = bc; }
;       if (half == 0) tots[col] = bc;
;       __syncthreads();
;       const float offs = half ? tots[col] : 0.f;
;     ...
;           pq[(size_t)j2 * NPROJ] = f2bf(qd); pk[(size_t)j2 * NPROJ] = kdb; kdT[(t0 + j2) * KD_PITCH + col] = kdb; }
	v_mul_f32_e32 v1, v33, v1
	s_waitcnt vmcnt(6)
	v_mul_f32_e32 v5, v32, v5
	s_waitcnt vmcnt(5)
	v_mul_f32_e32 v9, v25, v9
	s_waitcnt vmcnt(4)
	v_mul_f32_e32 v13, v21, v13
	v_fmac_f32_e32 v13, v19, v12
	v_fmac_f32_e32 v13, v20, v14
	v_fmac_f32_e32 v9, v23, v8
	v_fmac_f32_e32 v13, v18, v15
	v_fmac_f32_e32 v9, v24, v10
	v_fmac_f32_e32 v5, v27, v4
	v_add_f32_e32 v12, v34, v13
	v_fmac_f32_e32 v9, v22, v11
	v_fmac_f32_e32 v5, v28, v6
	v_fmac_f32_e32 v1, v30, v0
	v_add_f32_e32 v8, v12, v9
	v_fmac_f32_e32 v5, v26, v7
	v_fmac_f32_e32 v1, v31, v2
	v_add_f32_e32 v4, v8, v5
	v_fmac_f32_e32 v1, v29, v3
	v_add_f32_e32 v0, v4, v1
	v_min_f32_e32 v1, 0, v0
	v_mul_f32_e64 v0, |v0|, s59
	v_exp_f32_e32 v0, v0
	s_nop 0
	v_add_f32_e32 v0, 1.0, v0
	v_log_f32_e32 v0, v0
	s_nop 0
	v_mul_f32_e32 v2, 0x3f317217, v0
	v_fma_f32 v2, v0, s87, -v2
	v_fmac_f32_e32 v2, 0x3377d1cf, v0
	v_fmac_f32_e32 v2, 0x3f317217, v0
	v_sub_f32_e32 v0, v1, v2
	v_fmamk_f32 v249, v0, 0x3d800000, v248
	global_load_dwordx4 v[0:3], v67, s[98:99] offset:4048
	global_load_dwordx4 v[4:7], v67, s[98:99] offset:4032
	global_load_dwordx4 v[8:11], v67, s[98:99] offset:4016
	global_load_dwordx4 v[12:15], v67, s[98:99] offset:4000
	s_waitcnt vmcnt(7)
	v_mul_f32_e32 v71, v33, v71
	s_waitcnt vmcnt(6)
	v_mul_f32_e32 v75, v32, v75
	s_waitcnt vmcnt(5)
	v_mul_f32_e32 v79, v25, v79
	s_waitcnt vmcnt(4)
	v_mul_f32_e32 v83, v21, v83
	v_fmac_f32_e32 v83, v19, v82
	v_fmac_f32_e32 v83, v20, v84
	v_fmac_f32_e32 v79, v23, v78
	v_fmac_f32_e32 v83, v18, v85
	v_fmac_f32_e32 v79, v24, v80
	v_fmac_f32_e32 v75, v27, v74
	v_add_f32_e32 v82, v34, v83
	v_fmac_f32_e32 v79, v22, v81
	v_fmac_f32_e32 v75, v28, v76
	v_fmac_f32_e32 v71, v30, v70
	v_add_f32_e32 v78, v82, v79
	v_fmac_f32_e32 v75, v26, v77
	v_fmac_f32_e32 v71, v31, v72
	v_add_f32_e32 v74, v78, v75
	v_fmac_f32_e32 v71, v29, v73
	v_add_f32_e32 v70, v74, v71
	v_min_f32_e32 v71, 0, v70
	v_mul_f32_e64 v70, |v70|, s59
	v_exp_f32_e32 v70, v70
	s_nop 0
	v_add_f32_e32 v70, 1.0, v70
	v_log_f32_e32 v70, v70
	s_nop 0
	v_mul_f32_e32 v72, 0x3f317217, v70
	v_fma_f32 v72, v70, s87, -v72
	v_fmac_f32_e32 v72, 0x3377d1cf, v70
	v_fmac_f32_e32 v72, 0x3f317217, v70
	v_sub_f32_e32 v70, v71, v72
	v_fmamk_f32 v250, v70, 0x3d800000, v249
	s_movk_i32 s0, 0xff
	s_waitcnt vmcnt(3)
	v_mul_f32_e32 v1, v33, v1
	s_waitcnt vmcnt(2)
	v_mul_f32_e32 v5, v32, v5
	s_waitcnt vmcnt(1)
	v_mul_f32_e32 v9, v25, v9
	s_waitcnt vmcnt(0)
	v_mul_f32_e32 v13, v21, v13
	v_fmac_f32_e32 v13, v19, v12
	v_fmac_f32_e32 v13, v20, v14
	v_fmac_f32_e32 v9, v23, v8
	v_fmac_f32_e32 v13, v18, v15
	v_fmac_f32_e32 v9, v24, v10
	v_fmac_f32_e32 v5, v27, v4
	v_add_f32_e32 v12, v34, v13
	v_fmac_f32_e32 v9, v22, v11
	v_fmac_f32_e32 v5, v28, v6
	v_fmac_f32_e32 v1, v30, v0
	v_add_f32_e32 v8, v12, v9
	v_fmac_f32_e32 v5, v26, v7
	v_fmac_f32_e32 v1, v31, v2
	v_add_f32_e32 v4, v8, v5
	v_fmac_f32_e32 v1, v29, v3
	v_add_f32_e32 v0, v4, v1
	v_min_f32_e32 v1, 0, v0
	v_mul_f32_e64 v0, |v0|, s59
	v_exp_f32_e32 v0, v0
	s_nop 0
	v_add_f32_e32 v0, 1.0, v0
	v_log_f32_e32 v0, v0
	s_nop 0
	v_mul_f32_e32 v2, 0x3f317217, v0
	v_fma_f32 v2, v0, s87, -v2
	v_fmac_f32_e32 v2, 0x3377d1cf, v0
	v_fmac_f32_e32 v2, 0x3f317217, v0
	v_sub_f32_e32 v0, v1, v2
	v_cmp_lt_u32_e32 vcc, s0, v146
	s_movk_i32 s0, 0x100
	v_fmamk_f32 v251, v0, 0x3d800000, v250
	v_cmp_gt_u32_e64 s[38:39], s0, v146
	v_lshl_add_u32 v0, v219, 2, 0
	s_and_saveexec_b64 s[20:21], s[38:39]
	v_add_u32_e32 v1, 0x1d400, v0
	ds_write_b32 v1, v251
	s_or_b64 exec, exec, s[20:21]
	v_mov_b32_e32 v252, 0
	s_waitcnt lgkmcnt(0)
	s_barrier
	s_and_saveexec_b64 s[20:21], vcc
	v_add_u32_e32 v0, 0x1d400, v0
	ds_read_b32 v252, v0
	s_or_b64 exec, exec, s[20:21]
	s_mov_b64 s[0:1], 0xc00
	v_lshl_add_u64 v[50:51], v[16:17], 0, s[0:1]
	s_mov_b64 s[0:1], 0xe00
	v_lshl_add_u64 v[134:135], v[16:17], 0, s[0:1]
	s_mov_b64 s[0:1], 0x2600
	v_lshl_add_u64 v[130:131], v[16:17], 0, s[0:1]
	s_mov_b64 s[0:1], 0x2800
	v_lshl_add_u64 v[132:133], v[16:17], 0, s[0:1]
	s_mov_b64 s[0:1], 0x4000
	v_lshl_add_u64 v[126:127], v[16:17], 0, s[0:1]
	s_mov_b64 s[0:1], 0x4200
	v_lshl_add_u64 v[128:129], v[16:17], 0, s[0:1]
	s_mov_b64 s[0:1], 0x5a00
	v_lshl_add_u64 v[122:123], v[16:17], 0, s[0:1]
	s_mov_b64 s[0:1], 0x5c00
	v_lshl_add_u64 v[124:125], v[16:17], 0, s[0:1]
	s_mov_b64 s[0:1], 0x7400
	v_lshl_add_u64 v[118:119], v[16:17], 0, s[0:1]
	s_mov_b64 s[0:1], 0x7600
	v_lshl_add_u64 v[120:121], v[16:17], 0, s[0:1]
	s_mov_b64 s[0:1], 0x8e00
	v_lshl_add_u64 v[114:115], v[16:17], 0, s[0:1]
	s_mov_b64 s[0:1], 0x9000
	v_lshl_add_u64 v[116:117], v[16:17], 0, s[0:1]
	s_mov_b64 s[0:1], 0xa800
	v_lshl_add_u64 v[110:111], v[16:17], 0, s[0:1]
	s_mov_b64 s[0:1], 0xaa00
	v_lshl_add_u64 v[112:113], v[16:17], 0, s[0:1]
	s_mov_b64 s[0:1], 0xc200
	v_lshl_add_u64 v[106:107], v[16:17], 0, s[0:1]
	s_mov_b64 s[0:1], 0xc400
	v_lshl_add_u64 v[108:109], v[16:17], 0, s[0:1]
	s_mov_b64 s[0:1], 0xdc00
	v_lshl_add_u64 v[102:103], v[16:17], 0, s[0:1]
	s_mov_b64 s[0:1], 0xde00
	v_lshl_add_u64 v[104:105], v[16:17], 0, s[0:1]
	s_mov_b64 s[0:1], 0xf600
	v_lshl_add_u64 v[98:99], v[16:17], 0, s[0:1]
	s_mov_b64 s[0:1], 0xf800
	v_lshl_add_u64 v[100:101], v[16:17], 0, s[0:1]
	s_mov_b64 s[0:1], 0x11000
	v_lshl_add_u64 v[94:95], v[16:17], 0, s[0:1]
	s_mov_b64 s[0:1], 0x11200
	v_lshl_add_u64 v[96:97], v[16:17], 0, s[0:1]
	s_mov_b64 s[0:1], 0x12a00
	v_lshl_add_u64 v[90:91], v[16:17], 0, s[0:1]
	s_mov_b64 s[0:1], 0x12c00
	v_lshl_add_u64 v[92:93], v[16:17], 0, s[0:1]
	s_mov_b64 s[0:1], 0x14400
	v_lshl_add_u64 v[86:87], v[16:17], 0, s[0:1]
	s_mov_b64 s[0:1], 0x14600
	v_lshl_add_u64 v[88:89], v[16:17], 0, s[0:1]
	s_mov_b64 s[0:1], 0x15e00
	v_lshl_add_u64 v[82:83], v[16:17], 0, s[0:1]
; DI float bf2f(bf16_t u) { return __uint_as_float(((unsigned)u) << 16); }
; DI bf16_t f2bf(float f) { return (bf16_t)(pk2(f, 0.f) & 0xffffu); }
; DI void p2_unit(int chunk, const Params& p, LAS unsigned char* lds) {
;     ...
;       const float offs = half ? tots[col] : 0.f;
; #pragma unroll
;       for (int j2 = 0; j2 < 32; ++j2) { const float bcl = (offs + lc[j2]) * LOG2E;
;           const float qd = bf2f(qv32[j2]) * 0.125f * __builtin_amdgcn_exp2f(bcl), kd = bf2f(kv32[j2]) * __builtin_amdgcn_exp2f(-bcl);
;           const bf16_t kdb = f2bf(kd);
;           pq[(size_t)j2 * NPROJ] = f2bf(qd); pk[(size_t)j2 * NPROJ] = kdb; kdT[(t0 + j2) * KD_PITCH + col] = kdb; }
	s_mov_b64 s[0:1], 0x16000
	v_lshl_add_u64 v[84:85], v[16:17], 0, s[0:1]
	s_mov_b64 s[0:1], 0x17800
	v_lshl_add_u64 v[78:79], v[16:17], 0, s[0:1]
	s_mov_b64 s[0:1], 0x17a00
	v_lshl_add_u64 v[80:81], v[16:17], 0, s[0:1]
	s_mov_b64 s[0:1], 0x19200
	v_lshl_add_u64 v[74:75], v[16:17], 0, s[0:1]
	s_mov_b64 s[0:1], 0x19400
	v_lshl_add_u64 v[76:77], v[16:17], 0, s[0:1]
	s_mov_b64 s[0:1], 0x1ac00
	v_lshl_add_u64 v[70:71], v[16:17], 0, s[0:1]
	s_mov_b64 s[0:1], 0x1ae00
	v_lshl_add_u64 v[72:73], v[16:17], 0, s[0:1]
	s_mov_b64 s[0:1], 0x1c600
	v_lshl_add_u64 v[60:61], v[16:17], 0, s[0:1]
	s_mov_b64 s[0:1], 0x1c800
	v_lshl_add_u64 v[62:63], v[16:17], 0, s[0:1]
	s_mov_b64 s[0:1], 0x1e000
	v_lshl_add_u64 v[56:57], v[16:17], 0, s[0:1]
	s_mov_b64 s[0:1], 0x1e200
	v_lshl_add_u64 v[58:59], v[16:17], 0, s[0:1]
	s_mov_b64 s[0:1], 0x1fa00
	v_lshl_add_u64 v[52:53], v[16:17], 0, s[0:1]
	s_mov_b64 s[0:1], 0x1fc00
	v_lshl_add_u64 v[54:55], v[16:17], 0, s[0:1]
	s_mov_b64 s[0:1], 0x21400
	v_lshl_add_u64 v[46:47], v[16:17], 0, s[0:1]
	s_mov_b64 s[0:1], 0x21600
	v_lshl_add_u64 v[48:49], v[16:17], 0, s[0:1]
	s_mov_b64 s[0:1], 0x22e00
	v_lshl_add_u64 v[42:43], v[16:17], 0, s[0:1]
	s_mov_b64 s[0:1], 0x23000
	v_lshl_add_u64 v[44:45], v[16:17], 0, s[0:1]
	s_mov_b64 s[0:1], 0x24800
	v_lshl_add_u64 v[38:39], v[16:17], 0, s[0:1]
	s_mov_b64 s[0:1], 0x24a00
	v_lshl_add_u64 v[40:41], v[16:17], 0, s[0:1]
	s_mov_b64 s[0:1], 0x26200
	v_lshl_add_u64 v[34:35], v[16:17], 0, s[0:1]
	s_mov_b64 s[0:1], 0x26400
	v_lshl_add_u64 v[36:37], v[16:17], 0, s[0:1]
	s_mov_b64 s[0:1], 0x27c00
	v_lshl_add_u64 v[30:31], v[16:17], 0, s[0:1]
	s_mov_b64 s[0:1], 0x27e00
	v_lshl_add_u64 v[32:33], v[16:17], 0, s[0:1]
	s_mov_b64 s[0:1], 0x29600
	v_lshl_add_u64 v[26:27], v[16:17], 0, s[0:1]
	s_mov_b64 s[0:1], 0x29800
	v_lshl_add_u64 v[28:29], v[16:17], 0, s[0:1]
	s_mov_b64 s[0:1], 0x2b000
	v_lshl_add_u64 v[22:23], v[16:17], 0, s[0:1]
	s_mov_b64 s[0:1], 0x2b200
	v_lshl_add_u64 v[24:25], v[16:17], 0, s[0:1]
	s_mov_b64 s[0:1], 0x2ca00
	v_lshl_add_u64 v[18:19], v[16:17], 0, s[0:1]
	s_mov_b64 s[0:1], 0x2cc00
	v_lshl_add_u64 v[20:21], v[16:17], 0, s[0:1]
	s_mov_b64 s[0:1], 0x2e400
	v_lshl_add_u64 v[12:13], v[16:17], 0, s[0:1]
	s_mov_b64 s[0:1], 0x2e600
	v_lshl_add_u64 v[14:15], v[16:17], 0, s[0:1]
	s_mov_b64 s[0:1], 0x2fe00
	v_lshl_add_u64 v[8:9], v[16:17], 0, s[0:1]
	s_mov_b64 s[0:1], 0x30000
	v_lshl_add_u64 v[10:11], v[16:17], 0, s[0:1]
	s_mov_b64 s[0:1], 0x31800
	v_lshl_add_u64 v[4:5], v[16:17], 0, s[0:1]
	s_mov_b64 s[0:1], 0x31a00
	v_lshl_add_u64 v[6:7], v[16:17], 0, s[0:1]
	s_mov_b64 s[0:1], 0x33200
	v_lshl_add_u64 v[0:1], v[16:17], 0, s[0:1]
	s_mov_b64 s[0:1], 0x33400
	v_lshl_add_u64 v[2:3], v[16:17], 0, s[0:1]
	s_waitcnt lgkmcnt(0)
	v_add_f32_e32 v17, v220, v252
	s_add_i32 s0, 0, 0x12000
	v_mul_f32_e32 v17, 0x3fb8aa3b, v17
	v_lshl_add_u32 v16, v219, 1, s0
	v_exp_f32_e32 v219, v17
	v_exp_f32_e64 v17, -v17
	v_lshlrev_b32_e32 v218, 16, v218
	v_mul_f32_e32 v218, 0x3e000000, v218
	v_lshlrev_b32_e32 v217, 16, v217
	v_mul_f32_e32 v218, v218, v219
	v_mul_f32_e32 v17, v17, v217
	v_cvt_pk_bf16_f32 v17, v17, s0
	v_cvt_pk_bf16_f32 v217, v218, s0
	global_store_short v[50:51], v217, off
	global_store_short v[134:135], v17, off
	v_mad_u64_u32 v[50:51], s[0:1], v204, s88, v[16:17]
	ds_write_b16 v50, v17
	v_add_f32_e32 v17, v221, v252
	v_mul_f32_e32 v17, 0x3fb8aa3b, v17
	v_exp_f32_e32 v134, v17
	v_exp_f32_e64 v17, -v17
	v_lshlrev_b32_e32 v51, 16, v216
	v_mul_f32_e32 v51, 0x3e000000, v51
	v_mul_f32_e32 v51, v51, v134
	v_lshlrev_b32_e32 v134, 16, v215
	v_mul_f32_e32 v17, v17, v134
	v_cvt_pk_bf16_f32 v17, v17, s0
	v_cvt_pk_bf16_f32 v51, v51, s0
	global_store_short v[130:131], v51, off
	global_store_short v[132:133], v17, off
	ds_write_b16 v50, v17 offset:576
	v_add_f32_e32 v17, v222, v252
	v_mul_f32_e32 v17, 0x3fb8aa3b, v17
	v_exp_f32_e32 v130, v17
	v_exp_f32_e64 v17, -v17
	v_lshlrev_b32_e32 v51, 16, v214
	v_mul_f32_e32 v51, 0x3e000000, v51
	v_mul_f32_e32 v51, v51, v130
	v_lshlrev_b32_e32 v130, 16, v212
	v_mul_f32_e32 v17, v17, v130
	v_cvt_pk_bf16_f32 v17, v17, s0
	v_cvt_pk_bf16_f32 v51, v51, s0
	global_store_short v[126:127], v51, off
	global_store_short v[128:129], v17, off
	ds_write_b16 v50, v17 offset:1152
	v_add_f32_e32 v17, v223, v252
	v_mul_f32_e32 v17, 0x3fb8aa3b, v17
	v_exp_f32_e32 v126, v17
	v_exp_f32_e64 v17, -v17
	v_lshlrev_b32_e32 v51, 16, v213
	v_mul_f32_e32 v51, 0x3e000000, v51
	v_mul_f32_e32 v51, v51, v126
	v_lshlrev_b32_e32 v126, 16, v211
	v_mul_f32_e32 v17, v17, v126
	v_cvt_pk_bf16_f32 v17, v17, s0
	v_cvt_pk_bf16_f32 v51, v51, s0
	global_store_short v[122:123], v51, off
	global_store_short v[124:125], v17, off
	ds_write_b16 v50, v17 offset:1728
	v_add_f32_e32 v17, v224, v252
	v_mul_f32_e32 v17, 0x3fb8aa3b, v17
	v_exp_f32_e32 v122, v17
	v_exp_f32_e64 v17, -v17
	v_lshlrev_b32_e32 v51, 16, v210
	v_mul_f32_e32 v51, 0x3e000000, v51
	v_mul_f32_e32 v51, v51, v122
	v_lshlrev_b32_e32 v122, 16, v209
	v_mul_f32_e32 v17, v17, v122
	v_cvt_pk_bf16_f32 v17, v17, s0
	v_cvt_pk_bf16_f32 v51, v51, s0
	global_store_short v[118:119], v51, off
	global_store_short v[120:121], v17, off
	ds_write_b16 v50, v17 offset:2304
	v_add_f32_e32 v17, v225, v252
	v_mul_f32_e32 v17, 0x3fb8aa3b, v17
	v_exp_f32_e32 v118, v17
	v_exp_f32_e64 v17, -v17
	v_lshlrev_b32_e32 v51, 16, v207
	v_mul_f32_e32 v51, 0x3e000000, v51
	v_mul_f32_e32 v51, v51, v118
	v_lshlrev_b32_e32 v118, 16, v205
	v_mul_f32_e32 v17, v17, v118
	v_cvt_pk_bf16_f32 v17, v17, s0
	v_cvt_pk_bf16_f32 v51, v51, s0
	global_store_short v[114:115], v51, off
	global_store_short v[116:117], v17, off
	ds_write_b16 v50, v17 offset:2880
	v_add_f32_e32 v17, v226, v252
	v_mul_f32_e32 v17, 0x3fb8aa3b, v17
; DI float bf2f(bf16_t u) { return __uint_as_float(((unsigned)u) << 16); }
; DI bf16_t f2bf(float f) { return (bf16_t)(pk2(f, 0.f) & 0xffffu); }
; DI void p2_unit(int chunk, const Params& p, LAS unsigned char* lds) {
;     ...
;       for (int j2 = 0; j2 < 32; ++j2) { const float bcl = (offs + lc[j2]) * LOG2E;
;           const float qd = bf2f(qv32[j2]) * 0.125f * __builtin_amdgcn_exp2f(bcl), kd = bf2f(kv32[j2]) * __builtin_amdgcn_exp2f(-bcl);
;           const bf16_t kdb = f2bf(kd);
;           pq[(size_t)j2 * NPROJ] = f2bf(qd); pk[(size_t)j2 * NPROJ] = kdb; kdT[(t0 + j2) * KD_PITCH + col] = kdb; }
	v_exp_f32_e32 v114, v17
	v_exp_f32_e64 v17, -v17
	v_lshlrev_b32_e32 v51, 16, v203
	v_mul_f32_e32 v51, 0x3e000000, v51
	v_mul_f32_e32 v51, v51, v114
	v_lshlrev_b32_e32 v114, 16, v201
	v_mul_f32_e32 v17, v17, v114
	v_cvt_pk_bf16_f32 v17, v17, s0
	v_cvt_pk_bf16_f32 v51, v51, s0
	global_store_short v[110:111], v51, off
	global_store_short v[112:113], v17, off
	ds_write_b16 v50, v17 offset:3456
	v_add_f32_e32 v17, v227, v252
	v_mul_f32_e32 v17, 0x3fb8aa3b, v17
	v_exp_f32_e32 v110, v17
	v_exp_f32_e64 v17, -v17
	v_lshlrev_b32_e32 v51, 16, v202
	v_mul_f32_e32 v51, 0x3e000000, v51
	v_mul_f32_e32 v51, v51, v110
	v_lshlrev_b32_e32 v110, 16, v200
	v_mul_f32_e32 v17, v17, v110
	v_cvt_pk_bf16_f32 v17, v17, s0
	v_cvt_pk_bf16_f32 v51, v51, s0
	global_store_short v[106:107], v51, off
	global_store_short v[108:109], v17, off
	ds_write_b16 v50, v17 offset:4032
	v_add_f32_e32 v17, v228, v252
	v_mul_f32_e32 v17, 0x3fb8aa3b, v17
	v_exp_f32_e32 v106, v17
	v_exp_f32_e64 v17, -v17
	v_lshlrev_b32_e32 v51, 16, v199
	v_mul_f32_e32 v51, 0x3e000000, v51
	v_mul_f32_e32 v51, v51, v106
	v_lshlrev_b32_e32 v106, 16, v198
	v_mul_f32_e32 v17, v17, v106
	v_cvt_pk_bf16_f32 v17, v17, s0
	v_cvt_pk_bf16_f32 v51, v51, s0
	global_store_short v[102:103], v51, off
	global_store_short v[104:105], v17, off
	ds_write_b16 v50, v17 offset:4608
	v_add_f32_e32 v17, v229, v252
	v_mul_f32_e32 v17, 0x3fb8aa3b, v17
	v_exp_f32_e32 v102, v17
	v_exp_f32_e64 v17, -v17
	v_lshlrev_b32_e32 v51, 16, v197
	v_mul_f32_e32 v51, 0x3e000000, v51
	v_mul_f32_e32 v51, v51, v102
	v_lshlrev_b32_e32 v102, 16, v196
	v_mul_f32_e32 v17, v17, v102
	v_cvt_pk_bf16_f32 v17, v17, s0
	v_cvt_pk_bf16_f32 v51, v51, s0
	global_store_short v[98:99], v51, off
	global_store_short v[100:101], v17, off
	ds_write_b16 v50, v17 offset:5184
	v_add_f32_e32 v17, v230, v252
	v_mul_f32_e32 v17, 0x3fb8aa3b, v17
	v_exp_f32_e32 v98, v17
	v_exp_f32_e64 v17, -v17
	v_lshlrev_b32_e32 v51, 16, v195
	v_mul_f32_e32 v51, 0x3e000000, v51
	v_mul_f32_e32 v51, v51, v98
	v_lshlrev_b32_e32 v98, 16, v193
	v_mul_f32_e32 v17, v17, v98
	v_cvt_pk_bf16_f32 v17, v17, s0
	v_cvt_pk_bf16_f32 v51, v51, s0
	global_store_short v[94:95], v51, off
	global_store_short v[96:97], v17, off
	ds_write_b16 v50, v17 offset:5760
	v_add_f32_e32 v17, v231, v252
	v_mul_f32_e32 v17, 0x3fb8aa3b, v17
	v_exp_f32_e32 v94, v17
	v_exp_f32_e64 v17, -v17
	v_lshlrev_b32_e32 v51, 16, v194
	v_mul_f32_e32 v51, 0x3e000000, v51
	v_mul_f32_e32 v51, v51, v94
	v_lshlrev_b32_e32 v94, 16, v192
	v_mul_f32_e32 v17, v17, v94
	v_cvt_pk_bf16_f32 v17, v17, s0
	v_cvt_pk_bf16_f32 v51, v51, s0
	global_store_short v[90:91], v51, off
	global_store_short v[92:93], v17, off
	ds_write_b16 v50, v17 offset:6336
	v_add_f32_e32 v17, v232, v252
	v_mul_f32_e32 v17, 0x3fb8aa3b, v17
	v_exp_f32_e32 v90, v17
	v_exp_f32_e64 v17, -v17
	v_lshlrev_b32_e32 v51, 16, v191
	v_mul_f32_e32 v51, 0x3e000000, v51
	v_mul_f32_e32 v51, v51, v90
	v_lshlrev_b32_e32 v90, 16, v190
	v_mul_f32_e32 v17, v17, v90
	v_cvt_pk_bf16_f32 v17, v17, s0
	v_cvt_pk_bf16_f32 v51, v51, s0
	global_store_short v[86:87], v51, off
	global_store_short v[88:89], v17, off
	ds_write_b16 v50, v17 offset:6912
	v_add_f32_e32 v17, v233, v252
	v_mul_f32_e32 v17, 0x3fb8aa3b, v17
	v_exp_f32_e32 v86, v17
	v_exp_f32_e64 v17, -v17
	v_lshlrev_b32_e32 v51, 16, v189
	v_mul_f32_e32 v51, 0x3e000000, v51
	v_mul_f32_e32 v51, v51, v86
	v_lshlrev_b32_e32 v86, 16, v188
	v_mul_f32_e32 v17, v17, v86
	v_cvt_pk_bf16_f32 v17, v17, s0
	v_cvt_pk_bf16_f32 v51, v51, s0
	global_store_short v[82:83], v51, off
	global_store_short v[84:85], v17, off
	ds_write_b16 v50, v17 offset:7488
	v_add_f32_e32 v17, v234, v252
	v_mul_f32_e32 v17, 0x3fb8aa3b, v17
	v_exp_f32_e32 v82, v17
	v_exp_f32_e64 v17, -v17
	v_lshlrev_b32_e32 v51, 16, v187
	v_mul_f32_e32 v51, 0x3e000000, v51
	v_mul_f32_e32 v51, v51, v82
	v_lshlrev_b32_e32 v82, 16, v185
	v_mul_f32_e32 v17, v17, v82
	v_cvt_pk_bf16_f32 v17, v17, s0
	v_cvt_pk_bf16_f32 v51, v51, s0
	global_store_short v[78:79], v51, off
	global_store_short v[80:81], v17, off
	ds_write_b16 v50, v17 offset:8064
	v_add_f32_e32 v17, v235, v252
	v_mul_f32_e32 v17, 0x3fb8aa3b, v17
	v_exp_f32_e32 v78, v17
	v_exp_f32_e64 v17, -v17
	v_lshlrev_b32_e32 v51, 16, v186
	v_mul_f32_e32 v51, 0x3e000000, v51
	v_mul_f32_e32 v51, v51, v78
	v_lshlrev_b32_e32 v78, 16, v184
	v_mul_f32_e32 v17, v17, v78
	v_cvt_pk_bf16_f32 v17, v17, s0
	v_cvt_pk_bf16_f32 v51, v51, s0
	global_store_short v[74:75], v51, off
	global_store_short v[76:77], v17, off
	ds_write_b16 v50, v17 offset:8640
	v_add_f32_e32 v17, v236, v252
	v_mul_f32_e32 v17, 0x3fb8aa3b, v17
	v_exp_f32_e32 v74, v17
	v_exp_f32_e64 v17, -v17
	v_lshlrev_b32_e32 v51, 16, v183
	v_mul_f32_e32 v51, 0x3e000000, v51
	v_mul_f32_e32 v51, v51, v74
	v_lshlrev_b32_e32 v74, 16, v182
	v_mul_f32_e32 v17, v17, v74
	v_cvt_pk_bf16_f32 v17, v17, s0
	v_cvt_pk_bf16_f32 v51, v51, s0
	global_store_short v[70:71], v51, off
	global_store_short v[72:73], v17, off
	ds_write_b16 v50, v17 offset:9216
	v_add_f32_e32 v17, v237, v252
	v_mul_f32_e32 v17, 0x3fb8aa3b, v17
	v_exp_f32_e32 v70, v17
	v_exp_f32_e64 v17, -v17
	v_lshlrev_b32_e32 v51, 16, v181
	v_mul_f32_e32 v51, 0x3e000000, v51
	v_mul_f32_e32 v51, v51, v70
	v_lshlrev_b32_e32 v70, 16, v180
	v_mul_f32_e32 v17, v17, v70
	v_cvt_pk_bf16_f32 v17, v17, s0
	v_cvt_pk_bf16_f32 v51, v51, s0
	global_store_short v[60:61], v51, off
	global_store_short v[62:63], v17, off
	ds_write_b16 v50, v17 offset:9792
	v_add_f32_e32 v17, v238, v252
	v_mul_f32_e32 v17, 0x3fb8aa3b, v17
	v_exp_f32_e32 v60, v17
	v_exp_f32_e64 v17, -v17
	v_lshlrev_b32_e32 v51, 16, v179
	v_mul_f32_e32 v51, 0x3e000000, v51
	v_mul_f32_e32 v51, v51, v60
	v_lshlrev_b32_e32 v60, 16, v177
; DI float bf2f(bf16_t u) { return __uint_as_float(((unsigned)u) << 16); }
; DI bf16_t f2bf(float f) { return (bf16_t)(pk2(f, 0.f) & 0xffffu); }
; DI void p2_unit(int chunk, const Params& p, LAS unsigned char* lds) {
;     ...
;       for (int j2 = 0; j2 < 32; ++j2) { const float bcl = (offs + lc[j2]) * LOG2E;
;           const float qd = bf2f(qv32[j2]) * 0.125f * __builtin_amdgcn_exp2f(bcl), kd = bf2f(kv32[j2]) * __builtin_amdgcn_exp2f(-bcl);
;           const bf16_t kdb = f2bf(kd);
;           pq[(size_t)j2 * NPROJ] = f2bf(qd); pk[(size_t)j2 * NPROJ] = kdb; kdT[(t0 + j2) * KD_PITCH + col] = kdb; }
;       if (half) { const float dec = __builtin_amdgcn_exp2f((offs + bc) * LOG2E); decs[col] = dec; ((float*)(ws + WS_DECAY))[(size_t)(b * 128 + n) * 256 + col] = dec; }
	v_mul_f32_e32 v17, v17, v60
	v_cvt_pk_bf16_f32 v17, v17, s0
	v_cvt_pk_bf16_f32 v51, v51, s0
	global_store_short v[56:57], v51, off
	global_store_short v[58:59], v17, off
	ds_write_b16 v50, v17 offset:10368
	v_add_f32_e32 v17, v239, v252
	v_mul_f32_e32 v17, 0x3fb8aa3b, v17
	v_exp_f32_e32 v56, v17
	v_exp_f32_e64 v17, -v17
	v_lshlrev_b32_e32 v51, 16, v178
	v_mul_f32_e32 v51, 0x3e000000, v51
	v_mul_f32_e32 v51, v51, v56
	v_lshlrev_b32_e32 v56, 16, v176
	v_mul_f32_e32 v17, v17, v56
	v_cvt_pk_bf16_f32 v17, v17, s0
	v_cvt_pk_bf16_f32 v51, v51, s0
	global_store_short v[52:53], v51, off
	global_store_short v[54:55], v17, off
	ds_write_b16 v50, v17 offset:10944
	v_add_f32_e32 v17, v240, v252
	v_mul_f32_e32 v17, 0x3fb8aa3b, v17
	v_exp_f32_e32 v52, v17
	v_exp_f32_e64 v17, -v17
	v_lshlrev_b32_e32 v51, 16, v175
	v_mul_f32_e32 v51, 0x3e000000, v51
	v_mul_f32_e32 v51, v51, v52
	v_lshlrev_b32_e32 v52, 16, v174
	v_mul_f32_e32 v17, v17, v52
	v_cvt_pk_bf16_f32 v17, v17, s0
	v_cvt_pk_bf16_f32 v51, v51, s0
	global_store_short v[46:47], v51, off
	global_store_short v[48:49], v17, off
	ds_write_b16 v50, v17 offset:11520
	v_add_f32_e32 v17, v241, v252
	v_mul_f32_e32 v17, 0x3fb8aa3b, v17
	v_exp_f32_e32 v47, v17
	v_exp_f32_e64 v17, -v17
	v_lshlrev_b32_e32 v46, 16, v173
	v_mul_f32_e32 v46, 0x3e000000, v46
	v_mul_f32_e32 v46, v46, v47
	v_lshlrev_b32_e32 v47, 16, v172
	v_mul_f32_e32 v17, v17, v47
	v_cvt_pk_bf16_f32 v17, v17, s0
	v_cvt_pk_bf16_f32 v46, v46, s0
	global_store_short v[42:43], v46, off
	global_store_short v[44:45], v17, off
	ds_write_b16 v50, v17 offset:12096
	v_add_f32_e32 v17, v242, v252
	v_mul_f32_e32 v17, 0x3fb8aa3b, v17
	v_exp_f32_e32 v43, v17
	v_exp_f32_e64 v17, -v17
	v_lshlrev_b32_e32 v42, 16, v171
	v_mul_f32_e32 v42, 0x3e000000, v42
	v_mul_f32_e32 v42, v42, v43
	v_lshlrev_b32_e32 v43, 16, v170
	v_mul_f32_e32 v17, v17, v43
	v_cvt_pk_bf16_f32 v17, v17, s0
	v_cvt_pk_bf16_f32 v42, v42, s0
	global_store_short v[38:39], v42, off
	global_store_short v[40:41], v17, off
	ds_write_b16 v50, v17 offset:12672
	v_add_f32_e32 v17, v243, v252
	v_mul_f32_e32 v17, 0x3fb8aa3b, v17
	v_exp_f32_e32 v39, v17
	v_exp_f32_e64 v17, -v17
	v_lshlrev_b32_e32 v38, 16, v169
	v_mul_f32_e32 v38, 0x3e000000, v38
	v_mul_f32_e32 v38, v38, v39
	v_lshlrev_b32_e32 v39, 16, v168
	v_mul_f32_e32 v17, v17, v39
	v_cvt_pk_bf16_f32 v17, v17, s0
	v_cvt_pk_bf16_f32 v38, v38, s0
	global_store_short v[34:35], v38, off
	global_store_short v[36:37], v17, off
	ds_write_b16 v50, v17 offset:13248
	v_add_f32_e32 v17, v244, v252
	v_mul_f32_e32 v17, 0x3fb8aa3b, v17
	v_exp_f32_e32 v35, v17
	v_exp_f32_e64 v17, -v17
	v_lshlrev_b32_e32 v34, 16, v167
	v_mul_f32_e32 v34, 0x3e000000, v34
	v_mul_f32_e32 v34, v34, v35
	v_lshlrev_b32_e32 v35, 16, v166
	v_mul_f32_e32 v17, v17, v35
	v_cvt_pk_bf16_f32 v17, v17, s0
	v_cvt_pk_bf16_f32 v34, v34, s0
	global_store_short v[30:31], v34, off
	global_store_short v[32:33], v17, off
	ds_write_b16 v50, v17 offset:13824
	v_add_f32_e32 v17, v245, v252
	v_mul_f32_e32 v17, 0x3fb8aa3b, v17
	v_exp_f32_e32 v31, v17
	v_exp_f32_e64 v17, -v17
	v_lshlrev_b32_e32 v30, 16, v161
	v_mul_f32_e32 v30, 0x3e000000, v30
	v_mul_f32_e32 v30, v30, v31
	v_lshlrev_b32_e32 v31, 16, v160
	v_mul_f32_e32 v17, v17, v31
	v_cvt_pk_bf16_f32 v17, v17, s0
	v_cvt_pk_bf16_f32 v30, v30, s0
	global_store_short v[26:27], v30, off
	global_store_short v[28:29], v17, off
	ds_write_b16 v50, v17 offset:14400
	v_add_f32_e32 v17, v246, v252
	v_mul_f32_e32 v17, 0x3fb8aa3b, v17
	v_exp_f32_e32 v27, v17
	v_exp_f32_e64 v17, -v17
	v_lshlrev_b32_e32 v26, 16, v159
	v_mul_f32_e32 v26, 0x3e000000, v26
	v_mul_f32_e32 v26, v26, v27
	v_lshlrev_b32_e32 v27, 16, v158
	v_mul_f32_e32 v17, v17, v27
	v_cvt_pk_bf16_f32 v17, v17, s0
	v_cvt_pk_bf16_f32 v26, v26, s0
	global_store_short v[22:23], v26, off
	global_store_short v[24:25], v17, off
	ds_write_b16 v50, v17 offset:14976
	v_add_f32_e32 v17, v247, v252
	v_mul_f32_e32 v17, 0x3fb8aa3b, v17
	v_exp_f32_e32 v23, v17
	v_exp_f32_e64 v17, -v17
	v_lshlrev_b32_e32 v22, 16, v157
	v_mul_f32_e32 v22, 0x3e000000, v22
	v_mul_f32_e32 v22, v22, v23
	v_lshlrev_b32_e32 v23, 16, v156
	v_mul_f32_e32 v17, v17, v23
	v_cvt_pk_bf16_f32 v17, v17, s0
	v_cvt_pk_bf16_f32 v22, v22, s0
	global_store_short v[18:19], v22, off
	global_store_short v[20:21], v17, off
	ds_write_b16 v50, v17 offset:15552
	v_add_f32_e32 v17, v248, v252
	v_mul_f32_e32 v17, 0x3fb8aa3b, v17
	v_exp_f32_e32 v19, v17
	v_exp_f32_e64 v17, -v17
	v_lshlrev_b32_e32 v18, 16, v155
	v_mul_f32_e32 v18, 0x3e000000, v18
	v_mul_f32_e32 v18, v18, v19
	v_lshlrev_b32_e32 v19, 16, v154
	v_mul_f32_e32 v17, v17, v19
	v_cvt_pk_bf16_f32 v18, v18, s0
	v_cvt_pk_bf16_f32 v17, v17, s0
	global_store_short v[12:13], v18, off
	global_store_short v[14:15], v17, off
	v_add_f32_e32 v12, v249, v252
	v_mul_f32_e32 v12, 0x3fb8aa3b, v12
	v_exp_f32_e32 v14, v12
	v_exp_f32_e64 v12, -v12
	v_lshlrev_b32_e32 v13, 16, v153
	v_mul_f32_e32 v13, 0x3e000000, v13
	v_mul_f32_e32 v13, v13, v14
	v_lshlrev_b32_e32 v14, 16, v152
	v_mul_f32_e32 v12, v12, v14
	v_cvt_pk_bf16_f32 v13, v13, s0
	ds_write_b16 v50, v17 offset:16128
	v_cvt_pk_bf16_f32 v12, v12, s0
	global_store_short v[8:9], v13, off
	global_store_short v[10:11], v12, off
	v_add_f32_e32 v8, v250, v252
	v_mul_f32_e32 v8, 0x3fb8aa3b, v8
	v_exp_f32_e32 v10, v8
	v_exp_f32_e64 v8, -v8
	v_lshlrev_b32_e32 v9, 16, v151
	v_mul_f32_e32 v9, 0x3e000000, v9
	v_mul_f32_e32 v9, v9, v10
	v_lshlrev_b32_e32 v10, 16, v150
	v_mul_f32_e32 v8, v8, v10
	v_cvt_pk_bf16_f32 v9, v9, s0
	ds_write_b16 v50, v12 offset:16704
	v_cvt_pk_bf16_f32 v8, v8, s0
	global_store_short v[4:5], v9, off
	global_store_short v[6:7], v8, off
	v_add_f32_e32 v4, v251, v252
	v_mul_f32_e32 v5, 0x3fb8aa3b, v4
	v_lshlrev_b32_e32 v4, 16, v149
	v_mul_f32_e32 v6, 0x3e000000, v4
	v_exp_f32_e32 v4, v5
	v_exp_f32_e64 v5, -v5
	v_lshlrev_b32_e32 v7, 16, v148
	ds_write_b16 v50, v8 offset:17280
	v_mul_f32_e32 v6, v6, v4
	v_mul_f32_e32 v5, v5, v7
	v_cvt_pk_bf16_f32 v6, v6, s0
	v_cvt_pk_bf16_f32 v5, v5, s0
	global_store_short v[0:1], v6, off
	global_store_short v[2:3], v5, off
	v_or_b32_e32 v0, 31, v69
	v_mad_u64_u32 v[0:1], s[0:1], v0, s88, v[16:17]
	ds_write_b16 v0, v5
	s_and_saveexec_b64 s[20:21], vcc
	s_cbranch_execz .LBB0_347
	v_add_u32_e32 v0, 0, v66
	v_add_u32_e32 v0, 0x1d000, v0
	ds_write_b32 v0, v4
	global_store_dword v66, v4, s[64:65]
	s_branch .LBB0_347
